# K-loop: LDS-DMA destination M0 written directly as wave_offset+const (8 SALU per iteration removed in each of the five loops); previous edits
# baseline (speedup 1.0000x reference)
;     __device__ __forceinline__ void prefetch(const Unit& u, int wr, int wc, int lane) const { lnfold_prefetch(vl, stats, gW, bW, u, wr, wc, lane); }
;     __device__ __forceinline__ void prefetch(const Unit& u, int wr, int wc, int lane) const { lnfold_prefetch(vl, stats, gW, bW, u, wr, wc, lane); }
; #define PG8_STAGE(bufoff, gbase, voff) do { _Pragma("unroll") for (int _i = 0; _i < 2; ++_i) \
;         __builtin_amdgcn_global_load_lds((const unsigned*)((const char*)(gbase) + (voff)[_i]), (LAS unsigned*)(lds + (bufoff) + ldsw + _i * 8192), 16, 0, 0); } while (0)
; #define PG8_LDA(dst, b, h) do { _Pragma("unroll") for (int m = 0; m < 4; ++m) _Pragma("unroll") for (int k = 0; k < 2; ++k) dst[m][k] = *(const LAS f16x8*)(lds + PG8_SA(b, h) + aoff + m * 2048 + k * 1024); } while (0)
; #define PG8_LDB(dst, b, h) do { _Pragma("unroll") for (int n = 0; n < 2; ++n) _Pragma("unroll") for (int k = 0; k < 2; ++k) dst[n][k] = *(const LAS f16x8*)(lds + PG8_SB(b, h) + boff + n * 2048 + k * 1024); } while (0)
; #define PG8_WAIT_V(n) asm volatile("s_waitcnt vmcnt(" #n ")" ::: "memory")
; #define PG8_WAIT_L(n) asm volatile("s_waitcnt lgkmcnt(" #n ")" ::: "memory")
; template <class Epi>
; __device__ __forceinline__ void gemm_phase(LAS unsigned char* lds, const Gemm g0, const StaticOrder& S, const Epi& E) {
;     ...
;         for (int t = 0; t < nt; t += 2) {
;             const bool last = (t == nt - 2);
;             if (Epi::PREF && last) E.prefetch(cur, wr, wc, lane);
;             const char* a1 = cA + (size_t)(t + 1) * kstep;
;             const char* a2 = last ? nA : cA + (size_t)(t + 2) * kstep; const char* b2 = last ? nB : cB + (size_t)(t + 2) * kstep;
;             const char* a3 = a2 + kstep; const char* b3 = b2 + kstep;
;             PG8_LDB(B0, 0, 0); PG8_SCHED; PG8_LDA(At, 0, 0); PG8_STAGE(PG8_SA(1, 1), a1 + hstep, voffA);
;             PG8_WAIT_L(8); PG8_BAR; PG8_WAIT_L(0); PG8_MMA(0, 0, At, B0); PG8_BAR; PG8_SCHED;
;             PG8_LDB(B1, 0, 1); PG8_STAGE(PG8_SB(0, 0), b2, voffB);
;             PG8_BAR; PG8_WAIT_L(0); PG8_MMA(0, 1, At, B1); PG8_BAR;
;             PG8_LDA(At, 0, 1); PG8_STAGE(PG8_SA(0, 0), a2, voffA);
;             PG8_BAR; PG8_WAIT_L(0); PG8_MMA(1, 0, At, B0); PG8_BAR; PG8_SCHED;
;             PG8_STAGE(PG8_SB(0, 1), b2 + hstep, voffB);
;             PG8_WAIT_V(6); PG8_BAR; PG8_MMA(1, 1, At, B1); PG8_BAR;
.LBB0_198:
	s_add_u32 s52, s0, 0xfff80080
	s_addc_u32 s53, s1, -1
	s_and_b64 s[22:23], s[50:51], exec
	s_cselect_b32 s53, s75, s53
	s_cselect_b32 s52, s80, s52
	ds_read_b128 v[136:139], v161
	ds_read_b128 v[140:143], v161 offset:1024
	ds_read_b128 v[144:147], v161 offset:2048
	ds_read_b128 v[148:151], v161 offset:3072
	s_and_b64 s[22:23], s[50:51], exec
	s_cselect_b32 s51, s81, s25
	s_cselect_b32 s50, s82, s24
	s_add_i32 m0, s28, 0xc000
	ds_read_b128 v[152:155], v222
	ds_read_b128 v[156:159], v222 offset:1024
	ds_read_b128 v[186:189], v222 offset:2048
	ds_read_b128 v[190:193], v222 offset:3072
	ds_read_b128 v[194:197], v222 offset:4096
	ds_read_b128 v[198:201], v222 offset:5120
	ds_read_b128 v[202:205], v222 offset:6144
	ds_read_b128 v[206:209], v222 offset:7168
	global_load_lds_dwordx4 v184, s[0:1]
	s_add_i32 m0, s28, 0xe000
	s_nop 0
	global_load_lds_dwordx4 v182, s[0:1]
	s_waitcnt lgkmcnt(8)
	s_barrier
	s_waitcnt lgkmcnt(0)
	v_mfma_f32_16x16x32_f16 v[126:129], v[136:139], v[152:155], v[126:129]
	v_mfma_f32_16x16x32_f16 v[122:125], v[144:147], v[152:155], v[122:125]
	v_mfma_f32_16x16x32_f16 v[118:121], v[136:139], v[186:189], v[118:121]
	v_mfma_f32_16x16x32_f16 v[110:113], v[144:147], v[186:189], v[110:113]
	v_mfma_f32_16x16x32_f16 v[102:105], v[136:139], v[194:197], v[102:105]
	v_mfma_f32_16x16x32_f16 v[98:101], v[144:147], v[194:197], v[98:101]
	v_mfma_f32_16x16x32_f16 v[86:89], v[136:139], v[202:205], v[86:89]
	v_mfma_f32_16x16x32_f16 v[82:85], v[144:147], v[202:205], v[82:85]
	v_mfma_f32_16x16x32_f16 v[126:129], v[140:143], v[156:159], v[126:129]
	v_mfma_f32_16x16x32_f16 v[122:125], v[148:151], v[156:159], v[122:125]
	v_mfma_f32_16x16x32_f16 v[118:121], v[140:143], v[190:193], v[118:121]
	v_mfma_f32_16x16x32_f16 v[110:113], v[148:151], v[190:193], v[110:113]
	v_mfma_f32_16x16x32_f16 v[102:105], v[140:143], v[198:201], v[102:105]
	v_mfma_f32_16x16x32_f16 v[98:101], v[148:151], v[198:201], v[98:101]
	v_mfma_f32_16x16x32_f16 v[86:89], v[140:143], v[206:209], v[86:89]
	v_mfma_f32_16x16x32_f16 v[82:85], v[148:151], v[206:209], v[82:85]
	s_barrier
	ds_read_b128 v[210:213], v161 offset:16384
	ds_read_b128 v[234:237], v161 offset:17408
	ds_read_b128 v[238:241], v161 offset:18432
	s_add_i32 m0, s19, 0x10000
	ds_read_b128 v[242:245], v161 offset:19456
	global_load_lds_dwordx4 v178, s[50:51]
	s_add_i32 m0, s19, 0x12000
	s_nop 0
	global_load_lds_dwordx4 v174, s[50:51]
	s_barrier
	s_waitcnt lgkmcnt(0)
	v_mfma_f32_16x16x32_f16 v[114:117], v[210:213], v[152:155], v[114:117]
	v_mfma_f32_16x16x32_f16 v[106:109], v[238:241], v[152:155], v[106:109]
	v_mfma_f32_16x16x32_f16 v[94:97], v[210:213], v[186:189], v[94:97]
	v_mfma_f32_16x16x32_f16 v[90:93], v[238:241], v[186:189], v[90:93]
	v_mfma_f32_16x16x32_f16 v[78:81], v[210:213], v[194:197], v[78:81]
	v_mfma_f32_16x16x32_f16 v[74:77], v[238:241], v[194:197], v[74:77]
	v_mfma_f32_16x16x32_f16 v[70:73], v[210:213], v[202:205], v[70:73]
	v_mfma_f32_16x16x32_f16 v[66:69], v[238:241], v[202:205], v[66:69]
	v_mfma_f32_16x16x32_f16 v[114:117], v[234:237], v[156:159], v[114:117]
	v_mfma_f32_16x16x32_f16 v[106:109], v[242:245], v[156:159], v[106:109]
	v_mfma_f32_16x16x32_f16 v[94:97], v[234:237], v[190:193], v[94:97]
	v_mfma_f32_16x16x32_f16 v[90:93], v[242:245], v[190:193], v[90:93]
	v_mfma_f32_16x16x32_f16 v[78:81], v[234:237], v[198:201], v[78:81]
	v_mfma_f32_16x16x32_f16 v[74:77], v[242:245], v[198:201], v[74:77]
	v_mfma_f32_16x16x32_f16 v[70:73], v[234:237], v[206:209], v[70:73]
	v_mfma_f32_16x16x32_f16 v[66:69], v[242:245], v[206:209], v[66:69]
	s_mov_b32 m0, s28
	s_barrier
	ds_read_b128 v[152:155], v222 offset:16384
	ds_read_b128 v[156:159], v222 offset:17408
	ds_read_b128 v[186:189], v222 offset:18432
	ds_read_b128 v[190:193], v222 offset:19456
	ds_read_b128 v[194:197], v222 offset:20480
	ds_read_b128 v[198:201], v222 offset:21504
	ds_read_b128 v[202:205], v222 offset:22528
	ds_read_b128 v[206:209], v222 offset:23552
	global_load_lds_dwordx4 v180, s[52:53]
	s_mov_b32 m0, s29
	s_nop 0
	global_load_lds_dwordx4 v176, s[52:53]
	s_barrier
	s_waitcnt lgkmcnt(0)
	v_mfma_f32_16x16x32_f16 v[62:65], v[136:139], v[152:155], v[62:65]
	v_mfma_f32_16x16x32_f16 v[58:61], v[144:147], v[152:155], v[58:61]
	v_mfma_f32_16x16x32_f16 v[54:57], v[136:139], v[186:189], v[54:57]
	v_mfma_f32_16x16x32_f16 v[50:53], v[144:147], v[186:189], v[50:53]
	v_mfma_f32_16x16x32_f16 v[38:41], v[136:139], v[194:197], v[38:41]
	v_mfma_f32_16x16x32_f16 v[30:33], v[144:147], v[194:197], v[30:33]
	v_mfma_f32_16x16x32_f16 v[22:25], v[136:139], v[202:205], v[22:25]
	v_mfma_f32_16x16x32_f16 v[18:21], v[144:147], v[202:205], v[18:21]
	v_mfma_f32_16x16x32_f16 v[62:65], v[140:143], v[156:159], v[62:65]
	v_mfma_f32_16x16x32_f16 v[58:61], v[148:151], v[156:159], v[58:61]
	v_mfma_f32_16x16x32_f16 v[54:57], v[140:143], v[190:193], v[54:57]
	v_mfma_f32_16x16x32_f16 v[50:53], v[148:151], v[190:193], v[50:53]
	v_mfma_f32_16x16x32_f16 v[38:41], v[140:143], v[198:201], v[38:41]
	v_mfma_f32_16x16x32_f16 v[30:33], v[148:151], v[198:201], v[30:33]
	v_mfma_f32_16x16x32_f16 v[22:25], v[140:143], v[206:209], v[22:25]
	v_mfma_f32_16x16x32_f16 v[18:21], v[148:151], v[206:209], v[18:21]
	s_barrier
	s_add_u32 s22, s50, 0x80000
	s_addc_u32 s23, s51, 0
	s_add_i32 m0, s19, 0x14000
	s_nop 0
	global_load_lds_dwordx4 v178, s[22:23]
	s_add_i32 m0, s19, 0x16000
	s_nop 0
	global_load_lds_dwordx4 v174, s[22:23]
	s_waitcnt vmcnt(6)
	s_barrier
; #define PG8_STAGE(bufoff, gbase, voff) do { _Pragma("unroll") for (int _i = 0; _i < 2; ++_i) \
;         __builtin_amdgcn_global_load_lds((const unsigned*)((const char*)(gbase) + (voff)[_i]), (LAS unsigned*)(lds + (bufoff) + ldsw + _i * 8192), 16, 0, 0); } while (0)
; #define PG8_LDA(dst, b, h) do { _Pragma("unroll") for (int m = 0; m < 4; ++m) _Pragma("unroll") for (int k = 0; k < 2; ++k) dst[m][k] = *(const LAS f16x8*)(lds + PG8_SA(b, h) + aoff + m * 2048 + k * 1024); } while (0)
; #define PG8_LDB(dst, b, h) do { _Pragma("unroll") for (int n = 0; n < 2; ++n) _Pragma("unroll") for (int k = 0; k < 2; ++k) dst[n][k] = *(const LAS f16x8*)(lds + PG8_SB(b, h) + boff + n * 2048 + k * 1024); } while (0)
; #define PG8_MMA(ai, bj, At, Bt) do { __builtin_amdgcn_s_setprio(1); _Pragma("unroll") for (int m = 0; m < 4; ++m) _Pragma("unroll") for (int n = 0; n < 2; ++n) _Pragma("unroll") for (int k = 0; k < 2; ++k) \
;         acc[ai][bj][m][n] = __builtin_amdgcn_mfma_f32_16x16x32_f16(Bt[n][k], At[m][k], acc[ai][bj][m][n], 0, 0, 0); __builtin_amdgcn_s_setprio(0); } while (0)
; #define PG8_WAIT_V(n) asm volatile("s_waitcnt vmcnt(" #n ")" ::: "memory")
; #define PG8_WAIT_L(n) asm volatile("s_waitcnt lgkmcnt(" #n ")" ::: "memory")
; #define PG8_BAR __builtin_amdgcn_s_barrier()
; #define PG8_SCHED __builtin_amdgcn_sched_barrier(0)
; template <class Epi>
; __device__ __forceinline__ void gemm_phase(LAS unsigned char* lds, const Gemm g0, const StaticOrder& S, const Epi& E) {
;     ...
;             PG8_WAIT_V(6); PG8_BAR; PG8_MMA(1, 1, At, B1); PG8_BAR;
;             PG8_LDB(B0, 1, 0); PG8_SCHED; PG8_LDA(At, 1, 0); PG8_STAGE(PG8_SA(0, 1), a2 + hstep, voffA);
;             PG8_WAIT_L(8); PG8_BAR; PG8_WAIT_L(0); PG8_MMA(0, 0, At, B0); PG8_BAR; PG8_SCHED;
;             PG8_LDB(B1, 1, 1); PG8_STAGE(PG8_SB(1, 0), b3, voffB);
;             PG8_BAR; PG8_WAIT_L(0); PG8_MMA(0, 1, At, B1); PG8_BAR;
	v_mfma_f32_16x16x32_f16 v[46:49], v[210:213], v[152:155], v[46:49]
	v_mfma_f32_16x16x32_f16 v[42:45], v[238:241], v[152:155], v[42:45]
	v_mfma_f32_16x16x32_f16 v[34:37], v[210:213], v[186:189], v[34:37]
	v_mfma_f32_16x16x32_f16 v[26:29], v[238:241], v[186:189], v[26:29]
	v_mfma_f32_16x16x32_f16 v[14:17], v[210:213], v[194:197], v[14:17]
	v_mfma_f32_16x16x32_f16 v[10:13], v[238:241], v[194:197], v[10:13]
	v_mfma_f32_16x16x32_f16 v[6:9], v[210:213], v[202:205], v[6:9]
	v_mfma_f32_16x16x32_f16 v[2:5], v[238:241], v[202:205], v[2:5]
	v_mfma_f32_16x16x32_f16 v[46:49], v[234:237], v[156:159], v[46:49]
	v_mfma_f32_16x16x32_f16 v[42:45], v[242:245], v[156:159], v[42:45]
	v_mfma_f32_16x16x32_f16 v[34:37], v[234:237], v[190:193], v[34:37]
	v_mfma_f32_16x16x32_f16 v[26:29], v[242:245], v[190:193], v[26:29]
	v_mfma_f32_16x16x32_f16 v[14:17], v[234:237], v[198:201], v[14:17]
	v_mfma_f32_16x16x32_f16 v[10:13], v[242:245], v[198:201], v[10:13]
	v_mfma_f32_16x16x32_f16 v[6:9], v[234:237], v[206:209], v[6:9]
	v_mfma_f32_16x16x32_f16 v[2:5], v[242:245], v[206:209], v[2:5]
	s_barrier
	ds_read_b128 v[136:139], v161 offset:32768
	ds_read_b128 v[140:143], v161 offset:33792
	ds_read_b128 v[144:147], v161 offset:34816
	ds_read_b128 v[148:151], v161 offset:35840
	s_add_u32 s22, s52, 0x80000
	s_addc_u32 s23, s53, 0
	s_mov_b32 m0, s31
	ds_read_b128 v[152:155], v222 offset:32768
	ds_read_b128 v[156:159], v222 offset:33792
	ds_read_b128 v[186:189], v222 offset:34816
	ds_read_b128 v[190:193], v222 offset:35840
	ds_read_b128 v[194:197], v222 offset:36864
	ds_read_b128 v[198:201], v222 offset:37888
	ds_read_b128 v[202:205], v222 offset:38912
	ds_read_b128 v[206:209], v222 offset:39936
	global_load_lds_dwordx4 v180, s[22:23]
	s_mov_b32 m0, s58
	s_nop 0
	global_load_lds_dwordx4 v176, s[22:23]
	s_waitcnt lgkmcnt(8)
	s_barrier
	s_waitcnt lgkmcnt(0)
	v_mfma_f32_16x16x32_f16 v[126:129], v[136:139], v[152:155], v[126:129]
	v_mfma_f32_16x16x32_f16 v[122:125], v[144:147], v[152:155], v[122:125]
	v_mfma_f32_16x16x32_f16 v[118:121], v[136:139], v[186:189], v[118:121]
	v_mfma_f32_16x16x32_f16 v[110:113], v[144:147], v[186:189], v[110:113]
	v_mfma_f32_16x16x32_f16 v[102:105], v[136:139], v[194:197], v[102:105]
	v_mfma_f32_16x16x32_f16 v[98:101], v[144:147], v[194:197], v[98:101]
	v_mfma_f32_16x16x32_f16 v[86:89], v[136:139], v[202:205], v[86:89]
	v_mfma_f32_16x16x32_f16 v[82:85], v[144:147], v[202:205], v[82:85]
	v_mfma_f32_16x16x32_f16 v[126:129], v[140:143], v[156:159], v[126:129]
	v_mfma_f32_16x16x32_f16 v[122:125], v[148:151], v[156:159], v[122:125]
	v_mfma_f32_16x16x32_f16 v[118:121], v[140:143], v[190:193], v[118:121]
	v_mfma_f32_16x16x32_f16 v[110:113], v[148:151], v[190:193], v[110:113]
	v_mfma_f32_16x16x32_f16 v[102:105], v[140:143], v[198:201], v[102:105]
	v_mfma_f32_16x16x32_f16 v[98:101], v[148:151], v[198:201], v[98:101]
	v_mfma_f32_16x16x32_f16 v[86:89], v[140:143], v[206:209], v[86:89]
	v_mfma_f32_16x16x32_f16 v[82:85], v[148:151], v[206:209], v[82:85]
	s_barrier
	s_add_i32 m0, s19, 0x18000
	ds_read_b128 v[210:213], v161 offset:49152
	ds_read_b128 v[234:237], v161 offset:50176
	ds_read_b128 v[238:241], v161 offset:51200
	ds_read_b128 v[242:245], v161 offset:52224
	global_load_lds_dwordx4 v160, s[50:51]
	s_add_i32 m0, s19, 0x1a000
	s_nop 0
	global_load_lds_dwordx4 v162, s[50:51]
	s_barrier
; #define PG8_STAGE(bufoff, gbase, voff) do { _Pragma("unroll") for (int _i = 0; _i < 2; ++_i) \
;         __builtin_amdgcn_global_load_lds((const unsigned*)((const char*)(gbase) + (voff)[_i]), (LAS unsigned*)(lds + (bufoff) + ldsw + _i * 8192), 16, 0, 0); } while (0)
; #define PG8_LDA(dst, b, h) do { _Pragma("unroll") for (int m = 0; m < 4; ++m) _Pragma("unroll") for (int k = 0; k < 2; ++k) dst[m][k] = *(const LAS f16x8*)(lds + PG8_SA(b, h) + aoff + m * 2048 + k * 1024); } while (0)
; #define PG8_MMA(ai, bj, At, Bt) do { __builtin_amdgcn_s_setprio(1); _Pragma("unroll") for (int m = 0; m < 4; ++m) _Pragma("unroll") for (int n = 0; n < 2; ++n) _Pragma("unroll") for (int k = 0; k < 2; ++k) \
;         acc[ai][bj][m][n] = __builtin_amdgcn_mfma_f32_16x16x32_f16(Bt[n][k], At[m][k], acc[ai][bj][m][n], 0, 0, 0); __builtin_amdgcn_s_setprio(0); } while (0)
; #define PG8_WAIT_V(n) asm volatile("s_waitcnt vmcnt(" #n ")" ::: "memory")
; #define PG8_WAIT_L(n) asm volatile("s_waitcnt lgkmcnt(" #n ")" ::: "memory")
; #define PG8_BAR __builtin_amdgcn_s_barrier()
; #define PG8_SCHED __builtin_amdgcn_sched_barrier(0)
; template <class Epi>
; __device__ __forceinline__ void gemm_phase(LAS unsigned char* lds, const Gemm g0, const StaticOrder& S, const Epi& E) {
;     ...
;             PG8_BAR; PG8_WAIT_L(0); PG8_MMA(0, 1, At, B1); PG8_BAR;
;             PG8_LDA(At, 1, 1); PG8_STAGE(PG8_SA(1, 0), a3, voffA);
;             PG8_BAR; PG8_WAIT_L(0); PG8_MMA(1, 0, At, B0); PG8_BAR; PG8_SCHED;
;             PG8_STAGE(PG8_SB(1, 1), b3 + hstep, voffB);
;             PG8_WAIT_V(6); PG8_BAR; PG8_MMA(1, 1, At, B1); PG8_BAR;
;         }
	s_waitcnt lgkmcnt(0)
	v_mfma_f32_16x16x32_f16 v[114:117], v[210:213], v[152:155], v[114:117]
	v_mfma_f32_16x16x32_f16 v[106:109], v[238:241], v[152:155], v[106:109]
	v_mfma_f32_16x16x32_f16 v[94:97], v[210:213], v[186:189], v[94:97]
	v_mfma_f32_16x16x32_f16 v[90:93], v[238:241], v[186:189], v[90:93]
	v_mfma_f32_16x16x32_f16 v[78:81], v[210:213], v[194:197], v[78:81]
	v_mfma_f32_16x16x32_f16 v[74:77], v[238:241], v[194:197], v[74:77]
	v_mfma_f32_16x16x32_f16 v[70:73], v[210:213], v[202:205], v[70:73]
	v_mfma_f32_16x16x32_f16 v[66:69], v[238:241], v[202:205], v[66:69]
	v_mfma_f32_16x16x32_f16 v[114:117], v[234:237], v[156:159], v[114:117]
	v_mfma_f32_16x16x32_f16 v[106:109], v[242:245], v[156:159], v[106:109]
	v_mfma_f32_16x16x32_f16 v[94:97], v[234:237], v[190:193], v[94:97]
	v_mfma_f32_16x16x32_f16 v[90:93], v[242:245], v[190:193], v[90:93]
	v_mfma_f32_16x16x32_f16 v[78:81], v[234:237], v[198:201], v[78:81]
	v_mfma_f32_16x16x32_f16 v[74:77], v[242:245], v[198:201], v[74:77]
	v_mfma_f32_16x16x32_f16 v[70:73], v[234:237], v[206:209], v[70:73]
	v_mfma_f32_16x16x32_f16 v[66:69], v[242:245], v[206:209], v[66:69]
	s_mov_b32 m0, s59
	s_barrier
	ds_read_b128 v[152:155], v222 offset:49152
	ds_read_b128 v[156:159], v222 offset:50176
	ds_read_b128 v[186:189], v222 offset:51200
	ds_read_b128 v[190:193], v222 offset:52224
	ds_read_b128 v[194:197], v222 offset:53248
	ds_read_b128 v[198:201], v222 offset:54272
	ds_read_b128 v[202:205], v222 offset:55296
	ds_read_b128 v[206:209], v222 offset:56320
	global_load_lds_dwordx4 v164, s[52:53]
	s_mov_b32 m0, s61
	s_nop 0
	global_load_lds_dwordx4 v170, s[52:53]
	s_barrier
	s_waitcnt lgkmcnt(0)
	v_mfma_f32_16x16x32_f16 v[62:65], v[136:139], v[152:155], v[62:65]
	v_mfma_f32_16x16x32_f16 v[58:61], v[144:147], v[152:155], v[58:61]
	v_mfma_f32_16x16x32_f16 v[54:57], v[136:139], v[186:189], v[54:57]
	v_mfma_f32_16x16x32_f16 v[50:53], v[144:147], v[186:189], v[50:53]
	v_mfma_f32_16x16x32_f16 v[38:41], v[136:139], v[194:197], v[38:41]
	v_mfma_f32_16x16x32_f16 v[30:33], v[144:147], v[194:197], v[30:33]
	v_mfma_f32_16x16x32_f16 v[22:25], v[136:139], v[202:205], v[22:25]
	v_mfma_f32_16x16x32_f16 v[18:21], v[144:147], v[202:205], v[18:21]
	v_mfma_f32_16x16x32_f16 v[62:65], v[140:143], v[156:159], v[62:65]
	v_mfma_f32_16x16x32_f16 v[58:61], v[148:151], v[156:159], v[58:61]
	v_mfma_f32_16x16x32_f16 v[54:57], v[140:143], v[190:193], v[54:57]
	v_mfma_f32_16x16x32_f16 v[50:53], v[148:151], v[190:193], v[50:53]
	v_mfma_f32_16x16x32_f16 v[38:41], v[140:143], v[198:201], v[38:41]
	v_mfma_f32_16x16x32_f16 v[30:33], v[148:151], v[198:201], v[30:33]
	v_mfma_f32_16x16x32_f16 v[22:25], v[140:143], v[206:209], v[22:25]
	v_mfma_f32_16x16x32_f16 v[18:21], v[148:151], v[206:209], v[18:21]
	s_barrier
	s_add_u32 s22, s50, 0x80080
	s_addc_u32 s23, s51, 0
	s_add_i32 m0, s19, 0x1c000
	s_nop 0
	global_load_lds_dwordx4 v178, s[22:23]
	s_add_i32 m0, s19, 0x1e000
	s_nop 0
	global_load_lds_dwordx4 v174, s[22:23]
	s_waitcnt vmcnt(6)
	s_barrier
	v_mfma_f32_16x16x32_f16 v[46:49], v[210:213], v[152:155], v[46:49]
	v_mfma_f32_16x16x32_f16 v[42:45], v[238:241], v[152:155], v[42:45]
	v_mfma_f32_16x16x32_f16 v[34:37], v[210:213], v[186:189], v[34:37]
	v_mfma_f32_16x16x32_f16 v[26:29], v[238:241], v[186:189], v[26:29]
	v_mfma_f32_16x16x32_f16 v[14:17], v[210:213], v[194:197], v[14:17]
	v_mfma_f32_16x16x32_f16 v[10:13], v[238:241], v[194:197], v[10:13]
	v_mfma_f32_16x16x32_f16 v[6:9], v[210:213], v[202:205], v[6:9]
	v_mfma_f32_16x16x32_f16 v[2:5], v[238:241], v[202:205], v[2:5]
	v_mfma_f32_16x16x32_f16 v[46:49], v[234:237], v[156:159], v[46:49]
	v_mfma_f32_16x16x32_f16 v[42:45], v[242:245], v[156:159], v[42:45]
	v_mfma_f32_16x16x32_f16 v[34:37], v[234:237], v[190:193], v[34:37]
	v_mfma_f32_16x16x32_f16 v[26:29], v[242:245], v[190:193], v[26:29]
	v_mfma_f32_16x16x32_f16 v[14:17], v[234:237], v[198:201], v[14:17]
	v_mfma_f32_16x16x32_f16 v[10:13], v[242:245], v[198:201], v[10:13]
	v_mfma_f32_16x16x32_f16 v[6:9], v[234:237], v[206:209], v[6:9]
	v_mfma_f32_16x16x32_f16 v[2:5], v[242:245], v[206:209], v[2:5]
	s_add_i32 s83, s83, 2
	s_add_u32 s24, s24, 0x100
	s_addc_u32 s25, s25, 0
	s_add_u32 s0, s0, 0x100
	s_addc_u32 s1, s1, 0
	s_cmp_gt_u32 s83, 29
	s_barrier
	s_cbranch_scc1 .LBB0_201

;     __device__ __forceinline__ void prefetch(const Unit& u, int wr, int wc, int lane) const { lnfold_prefetch(vl, stats, gW, bW, u, wr, wc, lane); }
;     __device__ __forceinline__ void prefetch(const Unit& u, int wr, int wc, int lane) const { lnfold_prefetch(vl, stats, gW, bW, u, wr, wc, lane); }
; #define PG8_STAGE(bufoff, gbase, voff) do { _Pragma("unroll") for (int _i = 0; _i < 2; ++_i) \
;         __builtin_amdgcn_global_load_lds((const unsigned*)((const char*)(gbase) + (voff)[_i]), (LAS unsigned*)(lds + (bufoff) + ldsw + _i * 8192), 16, 0, 0); } while (0)
; #define PG8_LDA(dst, b, h) do { _Pragma("unroll") for (int m = 0; m < 4; ++m) _Pragma("unroll") for (int k = 0; k < 2; ++k) dst[m][k] = *(const LAS f16x8*)(lds + PG8_SA(b, h) + aoff + m * 2048 + k * 1024); } while (0)
; #define PG8_LDB(dst, b, h) do { _Pragma("unroll") for (int n = 0; n < 2; ++n) _Pragma("unroll") for (int k = 0; k < 2; ++k) dst[n][k] = *(const LAS f16x8*)(lds + PG8_SB(b, h) + boff + n * 2048 + k * 1024); } while (0)
; #define PG8_WAIT_V(n) asm volatile("s_waitcnt vmcnt(" #n ")" ::: "memory")
; #define PG8_WAIT_L(n) asm volatile("s_waitcnt lgkmcnt(" #n ")" ::: "memory")
; template <class Epi>
; __device__ __forceinline__ void gemm_phase(LAS unsigned char* lds, const Gemm g0, const StaticOrder& S, const Epi& E) {
;     ...
;         for (int t = 0; t < nt; t += 2) {
;             const bool last = (t == nt - 2);
;             if (Epi::PREF && last) E.prefetch(cur, wr, wc, lane);
;             const char* a1 = cA + (size_t)(t + 1) * kstep;
;             const char* a2 = last ? nA : cA + (size_t)(t + 2) * kstep; const char* b2 = last ? nB : cB + (size_t)(t + 2) * kstep;
;             const char* a3 = a2 + kstep; const char* b3 = b2 + kstep;
;             PG8_LDB(B0, 0, 0); PG8_SCHED; PG8_LDA(At, 0, 0); PG8_STAGE(PG8_SA(1, 1), a1 + hstep, voffA);
;             PG8_WAIT_L(8); PG8_BAR; PG8_WAIT_L(0); PG8_MMA(0, 0, At, B0); PG8_BAR; PG8_SCHED;
;             PG8_LDB(B1, 0, 1); PG8_STAGE(PG8_SB(0, 0), b2, voffB);
;             PG8_BAR; PG8_WAIT_L(0); PG8_MMA(0, 1, At, B1); PG8_BAR;
;             PG8_LDA(At, 0, 1); PG8_STAGE(PG8_SA(0, 0), a2, voffA);
;             PG8_BAR; PG8_WAIT_L(0); PG8_MMA(1, 0, At, B0); PG8_BAR; PG8_SCHED;
;             PG8_STAGE(PG8_SB(0, 1), b2 + hstep, voffB);
;             PG8_WAIT_V(6); PG8_BAR; PG8_MMA(1, 1, At, B1); PG8_BAR;
.LBB0_302:
	s_add_u32 s22, s6, 0xfff80080
	s_addc_u32 s23, s7, -1
	ds_read_b128 v[142:145], v161
	ds_read_b128 v[152:155], v161 offset:1024
	ds_read_b128 v[156:159], v161 offset:2048
	ds_read_b128 v[174:177], v161 offset:3072
	s_cmp_eq_u32 s58, 28
	s_cselect_b32 s37, s15, s23
	s_cselect_b32 s36, s52, s22
	s_cselect_b32 s35, s13, s53
	s_cselect_b32 s34, s24, s25
	s_add_i32 m0, s28, 0xc000
	ds_read_b128 v[178:181], v150
	ds_read_b128 v[182:185], v150 offset:1024
	ds_read_b128 v[186:189], v150 offset:2048
	ds_read_b128 v[190:193], v150 offset:3072
	ds_read_b128 v[194:197], v150 offset:4096
	ds_read_b128 v[198:201], v150 offset:5120
	ds_read_b128 v[202:205], v150 offset:6144
	ds_read_b128 v[206:209], v150 offset:7168
	global_load_lds_dwordx4 v140, s[6:7]
	s_add_i32 m0, s28, 0xe000
	s_nop 0
	global_load_lds_dwordx4 v138, s[6:7]
	s_waitcnt lgkmcnt(8)
	s_barrier
	s_waitcnt lgkmcnt(0)
	v_mfma_f32_16x16x32_f16 v[126:129], v[142:145], v[178:181], v[126:129]
	v_mfma_f32_16x16x32_f16 v[122:125], v[156:159], v[178:181], v[122:125]
	v_mfma_f32_16x16x32_f16 v[110:113], v[142:145], v[186:189], v[110:113]
	v_mfma_f32_16x16x32_f16 v[106:109], v[156:159], v[186:189], v[106:109]
	v_mfma_f32_16x16x32_f16 v[94:97], v[142:145], v[194:197], v[94:97]
	v_mfma_f32_16x16x32_f16 v[90:93], v[156:159], v[194:197], v[90:93]
	v_mfma_f32_16x16x32_f16 v[78:81], v[142:145], v[202:205], v[78:81]
	v_mfma_f32_16x16x32_f16 v[74:77], v[156:159], v[202:205], v[74:77]
	v_mfma_f32_16x16x32_f16 v[126:129], v[152:155], v[182:185], v[126:129]
	v_mfma_f32_16x16x32_f16 v[122:125], v[174:177], v[182:185], v[122:125]
	v_mfma_f32_16x16x32_f16 v[110:113], v[152:155], v[190:193], v[110:113]
	v_mfma_f32_16x16x32_f16 v[106:109], v[174:177], v[190:193], v[106:109]
	v_mfma_f32_16x16x32_f16 v[94:97], v[152:155], v[198:201], v[94:97]
	v_mfma_f32_16x16x32_f16 v[90:93], v[174:177], v[198:201], v[90:93]
	v_mfma_f32_16x16x32_f16 v[78:81], v[152:155], v[206:209], v[78:81]
	v_mfma_f32_16x16x32_f16 v[74:77], v[174:177], v[206:209], v[74:77]
	s_barrier
	ds_read_b128 v[210:213], v161 offset:16384
	ds_read_b128 v[234:237], v161 offset:17408
	ds_read_b128 v[238:241], v161 offset:18432
	s_add_i32 m0, s19, 0x10000
	ds_read_b128 v[242:245], v161 offset:19456
	global_load_lds_dwordx4 v134, s[34:35]
	s_add_i32 m0, s19, 0x12000
	s_nop 0
	global_load_lds_dwordx4 v130, s[34:35]
	s_barrier
	s_waitcnt lgkmcnt(0)
	v_mfma_f32_16x16x32_f16 v[118:121], v[210:213], v[178:181], v[118:121]
	v_mfma_f32_16x16x32_f16 v[114:117], v[238:241], v[178:181], v[114:117]
	v_mfma_f32_16x16x32_f16 v[102:105], v[210:213], v[186:189], v[102:105]
	v_mfma_f32_16x16x32_f16 v[98:101], v[238:241], v[186:189], v[98:101]
	v_mfma_f32_16x16x32_f16 v[86:89], v[210:213], v[194:197], v[86:89]
	v_mfma_f32_16x16x32_f16 v[82:85], v[238:241], v[194:197], v[82:85]
	v_mfma_f32_16x16x32_f16 v[70:73], v[210:213], v[202:205], v[70:73]
	v_mfma_f32_16x16x32_f16 v[66:69], v[238:241], v[202:205], v[66:69]
	v_mfma_f32_16x16x32_f16 v[118:121], v[234:237], v[182:185], v[118:121]
	v_mfma_f32_16x16x32_f16 v[114:117], v[242:245], v[182:185], v[114:117]
	v_mfma_f32_16x16x32_f16 v[102:105], v[234:237], v[190:193], v[102:105]
	v_mfma_f32_16x16x32_f16 v[98:101], v[242:245], v[190:193], v[98:101]
	v_mfma_f32_16x16x32_f16 v[86:89], v[234:237], v[198:201], v[86:89]
	v_mfma_f32_16x16x32_f16 v[82:85], v[242:245], v[198:201], v[82:85]
	v_mfma_f32_16x16x32_f16 v[70:73], v[234:237], v[206:209], v[70:73]
	v_mfma_f32_16x16x32_f16 v[66:69], v[242:245], v[206:209], v[66:69]
	s_mov_b32 m0, s28
	s_barrier
	ds_read_b128 v[178:181], v150 offset:16384
	ds_read_b128 v[182:185], v150 offset:17408
	ds_read_b128 v[186:189], v150 offset:18432
	ds_read_b128 v[190:193], v150 offset:19456
	ds_read_b128 v[194:197], v150 offset:20480
	ds_read_b128 v[198:201], v150 offset:21504
	ds_read_b128 v[202:205], v150 offset:22528
	ds_read_b128 v[206:209], v150 offset:23552
	global_load_lds_dwordx4 v136, s[36:37]
	s_mov_b32 m0, s29
	s_nop 0
	global_load_lds_dwordx4 v132, s[36:37]
	s_barrier
	s_waitcnt lgkmcnt(0)
	v_mfma_f32_16x16x32_f16 v[62:65], v[142:145], v[178:181], v[62:65]
	v_mfma_f32_16x16x32_f16 v[58:61], v[156:159], v[178:181], v[58:61]
	v_mfma_f32_16x16x32_f16 v[46:49], v[142:145], v[186:189], v[46:49]
	v_mfma_f32_16x16x32_f16 v[42:45], v[156:159], v[186:189], v[42:45]
	v_mfma_f32_16x16x32_f16 v[30:33], v[142:145], v[194:197], v[30:33]
	v_mfma_f32_16x16x32_f16 v[26:29], v[156:159], v[194:197], v[26:29]
	v_mfma_f32_16x16x32_f16 v[14:17], v[142:145], v[202:205], v[14:17]
	v_mfma_f32_16x16x32_f16 v[10:13], v[156:159], v[202:205], v[10:13]
	v_mfma_f32_16x16x32_f16 v[62:65], v[152:155], v[182:185], v[62:65]
	v_mfma_f32_16x16x32_f16 v[58:61], v[174:177], v[182:185], v[58:61]
	v_mfma_f32_16x16x32_f16 v[46:49], v[152:155], v[190:193], v[46:49]
	v_mfma_f32_16x16x32_f16 v[42:45], v[174:177], v[190:193], v[42:45]
	v_mfma_f32_16x16x32_f16 v[30:33], v[152:155], v[198:201], v[30:33]
	v_mfma_f32_16x16x32_f16 v[26:29], v[174:177], v[198:201], v[26:29]
	v_mfma_f32_16x16x32_f16 v[14:17], v[152:155], v[206:209], v[14:17]
	v_mfma_f32_16x16x32_f16 v[10:13], v[174:177], v[206:209], v[10:13]
	s_barrier
	s_add_u32 s22, s34, 0x80000
	s_addc_u32 s23, s35, 0
	s_add_i32 m0, s19, 0x14000
	s_nop 0
	global_load_lds_dwordx4 v134, s[22:23]
	s_add_i32 m0, s19, 0x16000
	s_nop 0
	global_load_lds_dwordx4 v130, s[22:23]
	s_waitcnt vmcnt(6)
	s_barrier
; #define PG8_STAGE(bufoff, gbase, voff) do { _Pragma("unroll") for (int _i = 0; _i < 2; ++_i) \
;         __builtin_amdgcn_global_load_lds((const unsigned*)((const char*)(gbase) + (voff)[_i]), (LAS unsigned*)(lds + (bufoff) + ldsw + _i * 8192), 16, 0, 0); } while (0)
; #define PG8_LDA(dst, b, h) do { _Pragma("unroll") for (int m = 0; m < 4; ++m) _Pragma("unroll") for (int k = 0; k < 2; ++k) dst[m][k] = *(const LAS f16x8*)(lds + PG8_SA(b, h) + aoff + m * 2048 + k * 1024); } while (0)
; #define PG8_LDB(dst, b, h) do { _Pragma("unroll") for (int n = 0; n < 2; ++n) _Pragma("unroll") for (int k = 0; k < 2; ++k) dst[n][k] = *(const LAS f16x8*)(lds + PG8_SB(b, h) + boff + n * 2048 + k * 1024); } while (0)
; #define PG8_MMA(ai, bj, At, Bt) do { __builtin_amdgcn_s_setprio(1); _Pragma("unroll") for (int m = 0; m < 4; ++m) _Pragma("unroll") for (int n = 0; n < 2; ++n) _Pragma("unroll") for (int k = 0; k < 2; ++k) \
;         acc[ai][bj][m][n] = __builtin_amdgcn_mfma_f32_16x16x32_f16(Bt[n][k], At[m][k], acc[ai][bj][m][n], 0, 0, 0); __builtin_amdgcn_s_setprio(0); } while (0)
; #define PG8_WAIT_V(n) asm volatile("s_waitcnt vmcnt(" #n ")" ::: "memory")
; #define PG8_WAIT_L(n) asm volatile("s_waitcnt lgkmcnt(" #n ")" ::: "memory")
; #define PG8_BAR __builtin_amdgcn_s_barrier()
; #define PG8_SCHED __builtin_amdgcn_sched_barrier(0)
; template <class Epi>
; __device__ __forceinline__ void gemm_phase(LAS unsigned char* lds, const Gemm g0, const StaticOrder& S, const Epi& E) {
;     ...
;             PG8_WAIT_V(6); PG8_BAR; PG8_MMA(1, 1, At, B1); PG8_BAR;
;             PG8_LDB(B0, 1, 0); PG8_SCHED; PG8_LDA(At, 1, 0); PG8_STAGE(PG8_SA(0, 1), a2 + hstep, voffA);
;             PG8_WAIT_L(8); PG8_BAR; PG8_WAIT_L(0); PG8_MMA(0, 0, At, B0); PG8_BAR; PG8_SCHED;
;             PG8_LDB(B1, 1, 1); PG8_STAGE(PG8_SB(1, 0), b3, voffB);
;             PG8_BAR; PG8_WAIT_L(0); PG8_MMA(0, 1, At, B1); PG8_BAR;
;             PG8_LDA(At, 1, 1); PG8_STAGE(PG8_SA(1, 0), a3, voffA);
	v_mfma_f32_16x16x32_f16 v[54:57], v[210:213], v[178:181], v[54:57]
	v_mfma_f32_16x16x32_f16 v[50:53], v[238:241], v[178:181], v[50:53]
	v_mfma_f32_16x16x32_f16 v[38:41], v[210:213], v[186:189], v[38:41]
	v_mfma_f32_16x16x32_f16 v[34:37], v[238:241], v[186:189], v[34:37]
	v_mfma_f32_16x16x32_f16 v[22:25], v[210:213], v[194:197], v[22:25]
	v_mfma_f32_16x16x32_f16 v[18:21], v[238:241], v[194:197], v[18:21]
	v_mfma_f32_16x16x32_f16 v[6:9], v[210:213], v[202:205], v[6:9]
	v_mfma_f32_16x16x32_f16 v[2:5], v[238:241], v[202:205], v[2:5]
	v_mfma_f32_16x16x32_f16 v[54:57], v[234:237], v[182:185], v[54:57]
	v_mfma_f32_16x16x32_f16 v[50:53], v[242:245], v[182:185], v[50:53]
	v_mfma_f32_16x16x32_f16 v[38:41], v[234:237], v[190:193], v[38:41]
	v_mfma_f32_16x16x32_f16 v[34:37], v[242:245], v[190:193], v[34:37]
	v_mfma_f32_16x16x32_f16 v[22:25], v[234:237], v[198:201], v[22:25]
	v_mfma_f32_16x16x32_f16 v[18:21], v[242:245], v[198:201], v[18:21]
	v_mfma_f32_16x16x32_f16 v[6:9], v[234:237], v[206:209], v[6:9]
	v_mfma_f32_16x16x32_f16 v[2:5], v[242:245], v[206:209], v[2:5]
	s_barrier
	ds_read_b128 v[142:145], v161 offset:32768
	ds_read_b128 v[152:155], v161 offset:33792
	ds_read_b128 v[156:159], v161 offset:34816
	ds_read_b128 v[174:177], v161 offset:35840
	s_add_u32 s22, s36, 0x80000
	s_addc_u32 s23, s37, 0
	s_mov_b32 m0, s31
	ds_read_b128 v[178:181], v150 offset:32768
	ds_read_b128 v[182:185], v150 offset:33792
	ds_read_b128 v[186:189], v150 offset:34816
	ds_read_b128 v[190:193], v150 offset:35840
	ds_read_b128 v[194:197], v150 offset:36864
	ds_read_b128 v[198:201], v150 offset:37888
	ds_read_b128 v[202:205], v150 offset:38912
	ds_read_b128 v[206:209], v150 offset:39936
	global_load_lds_dwordx4 v136, s[22:23]
	s_mov_b32 m0, s38
	s_nop 0
	global_load_lds_dwordx4 v132, s[22:23]
	s_waitcnt lgkmcnt(8)
	s_barrier
	s_waitcnt lgkmcnt(0)
	v_mfma_f32_16x16x32_f16 v[126:129], v[142:145], v[178:181], v[126:129]
	v_mfma_f32_16x16x32_f16 v[122:125], v[156:159], v[178:181], v[122:125]
	v_mfma_f32_16x16x32_f16 v[110:113], v[142:145], v[186:189], v[110:113]
	v_mfma_f32_16x16x32_f16 v[106:109], v[156:159], v[186:189], v[106:109]
	v_mfma_f32_16x16x32_f16 v[94:97], v[142:145], v[194:197], v[94:97]
	v_mfma_f32_16x16x32_f16 v[90:93], v[156:159], v[194:197], v[90:93]
	v_mfma_f32_16x16x32_f16 v[78:81], v[142:145], v[202:205], v[78:81]
	v_mfma_f32_16x16x32_f16 v[74:77], v[156:159], v[202:205], v[74:77]
	v_mfma_f32_16x16x32_f16 v[126:129], v[152:155], v[182:185], v[126:129]
	v_mfma_f32_16x16x32_f16 v[122:125], v[174:177], v[182:185], v[122:125]
	v_mfma_f32_16x16x32_f16 v[110:113], v[152:155], v[190:193], v[110:113]
	v_mfma_f32_16x16x32_f16 v[106:109], v[174:177], v[190:193], v[106:109]
	v_mfma_f32_16x16x32_f16 v[94:97], v[152:155], v[198:201], v[94:97]
	v_mfma_f32_16x16x32_f16 v[90:93], v[174:177], v[198:201], v[90:93]
	v_mfma_f32_16x16x32_f16 v[78:81], v[152:155], v[206:209], v[78:81]
	v_mfma_f32_16x16x32_f16 v[74:77], v[174:177], v[206:209], v[74:77]
	s_barrier
	s_add_i32 m0, s19, 0x18000
	ds_read_b128 v[210:213], v161 offset:49152
	ds_read_b128 v[234:237], v161 offset:50176
	ds_read_b128 v[238:241], v161 offset:51200
	ds_read_b128 v[242:245], v161 offset:52224
	global_load_lds_dwordx4 v146, s[34:35]
	s_add_i32 m0, s19, 0x1a000
	s_nop 0
	global_load_lds_dwordx4 v160, s[34:35]
	s_barrier
	s_waitcnt lgkmcnt(0)
	v_mfma_f32_16x16x32_f16 v[118:121], v[210:213], v[178:181], v[118:121]
	v_mfma_f32_16x16x32_f16 v[114:117], v[238:241], v[178:181], v[114:117]
	v_mfma_f32_16x16x32_f16 v[102:105], v[210:213], v[186:189], v[102:105]
	v_mfma_f32_16x16x32_f16 v[98:101], v[238:241], v[186:189], v[98:101]
	v_mfma_f32_16x16x32_f16 v[86:89], v[210:213], v[194:197], v[86:89]
	v_mfma_f32_16x16x32_f16 v[82:85], v[238:241], v[194:197], v[82:85]
	v_mfma_f32_16x16x32_f16 v[70:73], v[210:213], v[202:205], v[70:73]
	v_mfma_f32_16x16x32_f16 v[66:69], v[238:241], v[202:205], v[66:69]
	v_mfma_f32_16x16x32_f16 v[118:121], v[234:237], v[182:185], v[118:121]
	v_mfma_f32_16x16x32_f16 v[114:117], v[242:245], v[182:185], v[114:117]
	v_mfma_f32_16x16x32_f16 v[102:105], v[234:237], v[190:193], v[102:105]
	v_mfma_f32_16x16x32_f16 v[98:101], v[242:245], v[190:193], v[98:101]
	v_mfma_f32_16x16x32_f16 v[86:89], v[234:237], v[198:201], v[86:89]
	v_mfma_f32_16x16x32_f16 v[82:85], v[242:245], v[198:201], v[82:85]
	v_mfma_f32_16x16x32_f16 v[70:73], v[234:237], v[206:209], v[70:73]
	v_mfma_f32_16x16x32_f16 v[66:69], v[242:245], v[206:209], v[66:69]
	s_mov_b32 m0, s39
	s_barrier
	ds_read_b128 v[178:181], v150 offset:49152
	ds_read_b128 v[182:185], v150 offset:50176
	ds_read_b128 v[186:189], v150 offset:51200
	ds_read_b128 v[190:193], v150 offset:52224
	ds_read_b128 v[194:197], v150 offset:53248
	ds_read_b128 v[198:201], v150 offset:54272
	ds_read_b128 v[202:205], v150 offset:55296
	ds_read_b128 v[206:209], v150 offset:56320
	global_load_lds_dwordx4 v162, s[36:37]
	s_mov_b32 m0, s48
	s_nop 0
	global_load_lds_dwordx4 v164, s[36:37]
	s_barrier
; __device__ __forceinline__ float gelu_tanh(float x) { const float y = 1.5957691216057308f * (x + 0.044715f * x * x * x); return x * fast_rcp(1.0f + __expf(-y)); }
; #define PG8_STAGE(bufoff, gbase, voff) do { _Pragma("unroll") for (int _i = 0; _i < 2; ++_i) \
;         __builtin_amdgcn_global_load_lds((const unsigned*)((const char*)(gbase) + (voff)[_i]), (LAS unsigned*)(lds + (bufoff) + ldsw + _i * 8192), 16, 0, 0); } while (0)
; #define PG8_LDA(dst, b, h) do { _Pragma("unroll") for (int m = 0; m < 4; ++m) _Pragma("unroll") for (int k = 0; k < 2; ++k) dst[m][k] = *(const LAS f16x8*)(lds + PG8_SA(b, h) + aoff + m * 2048 + k * 1024); } while (0)
; #define PG8_MMA(ai, bj, At, Bt) do { __builtin_amdgcn_s_setprio(1); _Pragma("unroll") for (int m = 0; m < 4; ++m) _Pragma("unroll") for (int n = 0; n < 2; ++n) _Pragma("unroll") for (int k = 0; k < 2; ++k) \
;         acc[ai][bj][m][n] = __builtin_amdgcn_mfma_f32_16x16x32_f16(Bt[n][k], At[m][k], acc[ai][bj][m][n], 0, 0, 0); __builtin_amdgcn_s_setprio(0); } while (0)
; #define PG8_WAIT_V(n) asm volatile("s_waitcnt vmcnt(" #n ")" ::: "memory")
;     __device__ __forceinline__ void operator()(f32x4 (&acc)[2][2][4][2], const Unit& u, int wr, int wc, int fr, int fq) const {
;         const bool isy = u.pn < 8; h16* dst = isy ? ybr : xpre; const int colb = (isy ? u.pn : u.pn - 8) * BM + wc * 32 + 8 * fq;
;         const int row0 = u.pm * BM + wr * 64 + fr;
; #pragma unroll
;         for (int ai = 0; ai < 2; ++ai)
; #pragma unroll
;             for (int m = 0; m < 4; ++m) { h16* rowp = dst + (size_t)(row0 + ai * HALF + m * 16) * DM + colb;
; #pragma unroll
;                 for (int bj = 0; bj < 2; ++bj) { f32x4 v0 = acc[ai][bj][m][0], v1 = acc[ai][bj][m][1];
;                     if (isy) {
; #pragma unroll
;                         for (int j = 0; j < 4; ++j) { v0[j] = gelu_tanh(v0[j]); v1[j] = gelu_tanh(v1[j]); } }
; template <class Epi>
; __device__ __forceinline__ void gemm_phase(LAS unsigned char* lds, const Gemm g0, const StaticOrder& S, const Epi& E) {
;     ...
;             PG8_BAR; PG8_WAIT_L(0); PG8_MMA(0, 1, At, B1); PG8_BAR;
;             PG8_LDA(At, 1, 1); PG8_STAGE(PG8_SA(1, 0), a3, voffA);
;             PG8_BAR; PG8_WAIT_L(0); PG8_MMA(1, 0, At, B0); PG8_BAR; PG8_SCHED;
;             PG8_STAGE(PG8_SB(1, 1), b3 + hstep, voffB);
;             PG8_WAIT_V(6); PG8_BAR; PG8_MMA(1, 1, At, B1); PG8_BAR;
;         }
	s_waitcnt lgkmcnt(0)
	v_mfma_f32_16x16x32_f16 v[62:65], v[142:145], v[178:181], v[62:65]
	v_mfma_f32_16x16x32_f16 v[58:61], v[156:159], v[178:181], v[58:61]
	v_mfma_f32_16x16x32_f16 v[46:49], v[142:145], v[186:189], v[46:49]
	v_mfma_f32_16x16x32_f16 v[42:45], v[156:159], v[186:189], v[42:45]
	v_mfma_f32_16x16x32_f16 v[30:33], v[142:145], v[194:197], v[30:33]
	v_mfma_f32_16x16x32_f16 v[26:29], v[156:159], v[194:197], v[26:29]
	v_mfma_f32_16x16x32_f16 v[14:17], v[142:145], v[202:205], v[14:17]
	v_mfma_f32_16x16x32_f16 v[10:13], v[156:159], v[202:205], v[10:13]
	v_mfma_f32_16x16x32_f16 v[62:65], v[152:155], v[182:185], v[62:65]
	v_mfma_f32_16x16x32_f16 v[58:61], v[174:177], v[182:185], v[58:61]
	v_mfma_f32_16x16x32_f16 v[46:49], v[152:155], v[190:193], v[46:49]
	v_mfma_f32_16x16x32_f16 v[42:45], v[174:177], v[190:193], v[42:45]
	v_mfma_f32_16x16x32_f16 v[30:33], v[152:155], v[198:201], v[30:33]
	v_mfma_f32_16x16x32_f16 v[26:29], v[174:177], v[198:201], v[26:29]
	v_mfma_f32_16x16x32_f16 v[14:17], v[152:155], v[206:209], v[14:17]
	v_mfma_f32_16x16x32_f16 v[10:13], v[174:177], v[206:209], v[10:13]
	s_barrier
	s_add_u32 s22, s34, 0x80080
	s_addc_u32 s23, s35, 0
	s_add_i32 m0, s19, 0x1c000
	s_nop 0
	global_load_lds_dwordx4 v134, s[22:23]
	s_add_i32 m0, s19, 0x1e000
	s_nop 0
	global_load_lds_dwordx4 v130, s[22:23]
	s_waitcnt vmcnt(6)
	s_barrier
	v_mfma_f32_16x16x32_f16 v[54:57], v[210:213], v[178:181], v[54:57]
	v_mfma_f32_16x16x32_f16 v[50:53], v[238:241], v[178:181], v[50:53]
	v_mfma_f32_16x16x32_f16 v[38:41], v[210:213], v[186:189], v[38:41]
	v_mfma_f32_16x16x32_f16 v[34:37], v[238:241], v[186:189], v[34:37]
	v_mfma_f32_16x16x32_f16 v[22:25], v[210:213], v[194:197], v[22:25]
	v_mfma_f32_16x16x32_f16 v[18:21], v[238:241], v[194:197], v[18:21]
	v_mfma_f32_16x16x32_f16 v[6:9], v[210:213], v[202:205], v[6:9]
	v_mfma_f32_16x16x32_f16 v[2:5], v[238:241], v[202:205], v[2:5]
	v_mfma_f32_16x16x32_f16 v[54:57], v[234:237], v[182:185], v[54:57]
	v_mfma_f32_16x16x32_f16 v[50:53], v[242:245], v[182:185], v[50:53]
	v_mfma_f32_16x16x32_f16 v[38:41], v[234:237], v[190:193], v[38:41]
	v_mfma_f32_16x16x32_f16 v[34:37], v[242:245], v[190:193], v[34:37]
	v_mfma_f32_16x16x32_f16 v[22:25], v[234:237], v[198:201], v[22:25]
	v_mfma_f32_16x16x32_f16 v[18:21], v[242:245], v[198:201], v[18:21]
	v_mfma_f32_16x16x32_f16 v[6:9], v[234:237], v[206:209], v[6:9]
	v_mfma_f32_16x16x32_f16 v[2:5], v[242:245], v[206:209], v[2:5]
	s_add_i32 s58, s58, 2
	s_add_u32 s25, s25, 0x100
	s_addc_u32 s53, s53, 0
	s_add_u32 s6, s6, 0x100
	s_addc_u32 s7, s7, 0
	s_cmp_gt_u32 s58, 29
	s_barrier
	s_cbranch_scc0 .LBB0_302
	s_cmp_lt_i32 s51, 8
	s_cselect_b64 s[34:35], -1, 0
	s_cmp_gt_i32 s51, 7
	s_cbranch_scc1 .LBB0_305
	v_mul_f32_e32 v143, 0x3d372713, v122
	v_mul_f32_e32 v143, v122, v143
	v_fma_f32 v143, v122, v143, v122
	v_mul_f32_e32 v143, 0xbfcc422a, v143
	v_mul_f32_e32 v143, 0x3fb8aa3b, v143
	v_exp_f32_e32 v143, v143
	v_mul_f32_e32 v142, 0x3d372713, v126
	v_mul_f32_e32 v142, v126, v142
	v_fma_f32 v142, v126, v142, v126
	v_add_f32_e32 v143, 1.0, v143
	v_rcp_f32_e32 v144, v143
	v_mul_f32_e32 v143, 0x3d372713, v127
	v_mul_f32_e32 v143, v127, v143
	v_fma_f32 v143, v127, v143, v127
	v_mul_f32_e32 v142, 0xbfcc422a, v142
	v_mul_f32_e32 v143, 0xbfcc422a, v143
	v_mul_f32_e32 v142, 0x3fb8aa3b, v142
	v_mul_f32_e32 v143, 0x3fb8aa3b, v143
	v_mul_f32_e32 v147, 0x3d372713, v124
	v_exp_f32_e32 v142, v142
	v_exp_f32_e32 v143, v143
	v_mul_f32_e32 v147, v124, v147
	v_fma_f32 v147, v124, v147, v124
	v_mul_f32_e32 v147, 0xbfcc422a, v147
	v_mul_f32_e32 v147, 0x3fb8aa3b, v147
	v_add_f32_e32 v142, 1.0, v142
	v_add_f32_e32 v143, 1.0, v143
	v_exp_f32_e32 v147, v147
	v_rcp_f32_e32 v142, v142
	v_rcp_f32_e32 v143, v143
	v_mul_f32_e32 v145, 0x3d372713, v123
	v_add_f32_e32 v147, 1.0, v147
	v_mul_f32_e32 v146, 0x3d372713, v128
	v_rcp_f32_e32 v152, v147
	v_mul_f32_e32 v147, 0x3d372713, v129
	v_pk_mul_f32 v[126:127], v[126:127], v[142:143]
	v_mul_f32_e32 v142, 0x3d372713, v125
	v_mul_f32_e32 v145, v123, v145
	v_mul_f32_e32 v146, v128, v146
	v_mul_f32_e32 v147, v129, v147
	v_mul_f32_e32 v142, v125, v142
	v_fma_f32 v145, v123, v145, v123
	v_fma_f32 v146, v128, v146, v128
	v_fma_f32 v147, v129, v147, v129
	v_fma_f32 v142, v125, v142, v125
	v_mul_f32_e32 v145, 0xbfcc422a, v145
	v_mul_f32_e32 v146, 0xbfcc422a, v146
	v_mul_f32_e32 v147, 0xbfcc422a, v147
	v_mul_f32_e32 v142, 0xbfcc422a, v142
	v_mul_f32_e32 v145, 0x3fb8aa3b, v145
	v_mul_f32_e32 v146, 0x3fb8aa3b, v146
	v_mul_f32_e32 v147, 0x3fb8aa3b, v147
	v_mul_f32_e32 v142, 0x3fb8aa3b, v142
	v_exp_f32_e32 v145, v145
	v_exp_f32_e32 v146, v146
	v_exp_f32_e32 v147, v147
	v_exp_f32_e32 v142, v142
	v_add_f32_e32 v145, 1.0, v145
	v_add_f32_e32 v146, 1.0, v146
	v_add_f32_e32 v147, 1.0, v147
	v_add_f32_e32 v142, 1.0, v142
	v_rcp_f32_e32 v145, v145
	v_rcp_f32_e32 v146, v146
	v_rcp_f32_e32 v147, v147
	v_rcp_f32_e32 v153, v142
	v_pk_mul_f32 v[122:123], v[122:123], v[144:145]
	v_pk_mul_f32 v[128:129], v[128:129], v[146:147]
	v_pk_mul_f32 v[124:125], v[124:125], v[152:153]

;     __device__ __forceinline__ void prefetch(const Unit& u, int wr, int wc, int lane) const { lnfold_prefetch(vl, stats, gW, bW, u, wr, wc, lane); }
;     __device__ __forceinline__ void prefetch(const Unit& u, int wr, int wc, int lane) const { lnfold_prefetch(vl, stats, gW, bW, u, wr, wc, lane); }
; #define PG8_STAGE(bufoff, gbase, voff) do { _Pragma("unroll") for (int _i = 0; _i < 2; ++_i) \
;         __builtin_amdgcn_global_load_lds((const unsigned*)((const char*)(gbase) + (voff)[_i]), (LAS unsigned*)(lds + (bufoff) + ldsw + _i * 8192), 16, 0, 0); } while (0)
; #define PG8_LDA(dst, b, h) do { _Pragma("unroll") for (int m = 0; m < 4; ++m) _Pragma("unroll") for (int k = 0; k < 2; ++k) dst[m][k] = *(const LAS f16x8*)(lds + PG8_SA(b, h) + aoff + m * 2048 + k * 1024); } while (0)
; #define PG8_LDB(dst, b, h) do { _Pragma("unroll") for (int n = 0; n < 2; ++n) _Pragma("unroll") for (int k = 0; k < 2; ++k) dst[n][k] = *(const LAS f16x8*)(lds + PG8_SB(b, h) + boff + n * 2048 + k * 1024); } while (0)
; #define PG8_WAIT_V(n) asm volatile("s_waitcnt vmcnt(" #n ")" ::: "memory")
; #define PG8_WAIT_L(n) asm volatile("s_waitcnt lgkmcnt(" #n ")" ::: "memory")
; #define PG8_BAR __builtin_amdgcn_s_barrier()
; template <class Epi>
; __device__ __forceinline__ void gemm_phase(LAS unsigned char* lds, const Gemm g0, const StaticOrder& S, const Epi& E) {
;     ...
;             const bool last = (t == nt - 2);
;             if (Epi::PREF && last) E.prefetch(cur, wr, wc, lane);
;             const char* a1 = cA + (size_t)(t + 1) * kstep;
;             const char* a2 = last ? nA : cA + (size_t)(t + 2) * kstep; const char* b2 = last ? nB : cB + (size_t)(t + 2) * kstep;
;             const char* a3 = a2 + kstep; const char* b3 = b2 + kstep;
;             PG8_LDB(B0, 0, 0); PG8_SCHED; PG8_LDA(At, 0, 0); PG8_STAGE(PG8_SA(1, 1), a1 + hstep, voffA);
;             PG8_WAIT_L(8); PG8_BAR; PG8_WAIT_L(0); PG8_MMA(0, 0, At, B0); PG8_BAR; PG8_SCHED;
;             PG8_LDB(B1, 0, 1); PG8_STAGE(PG8_SB(0, 0), b2, voffB);
;             PG8_BAR; PG8_WAIT_L(0); PG8_MMA(0, 1, At, B1); PG8_BAR;
;             PG8_LDA(At, 0, 1); PG8_STAGE(PG8_SA(0, 0), a2, voffA);
;             PG8_BAR; PG8_WAIT_L(0); PG8_MMA(1, 0, At, B0); PG8_BAR; PG8_SCHED;
;             PG8_STAGE(PG8_SB(0, 1), b2 + hstep, voffB);
;             PG8_WAIT_V(6); PG8_BAR; PG8_MMA(1, 1, At, B1); PG8_BAR;
.LBB0_512:
	s_add_u32 s23, s12, 0xfff80080
	s_addc_u32 s48, s13, -1
	ds_read_b128 v[122:125], v165
	ds_read_b128 v[126:129], v165 offset:1024
	ds_read_b128 v[138:141], v165 offset:2048
	ds_read_b128 v[142:145], v165 offset:3072
	s_cmp_eq_u32 s22, 28
	s_cselect_b32 s51, s15, s48
	s_cselect_b32 s50, s24, s23
	s_cselect_b32 s49, s25, vcc_hi
	s_cselect_b32 s48, s53, vcc_lo
	s_add_i32 m0, s71, 0xc000
	ds_read_b128 v[146:149], v210
	ds_read_b128 v[150:153], v210 offset:1024
	ds_read_b128 v[154:157], v210 offset:2048
	ds_read_b128 v[158:161], v210 offset:3072
	ds_read_b128 v[188:191], v210 offset:4096
	ds_read_b128 v[192:195], v210 offset:5120
	ds_read_b128 v[196:199], v210 offset:6144
	ds_read_b128 v[200:203], v210 offset:7168
	global_load_lds_dwordx4 v186, s[12:13]
	s_add_i32 m0, s71, 0xe000
	s_nop 0
	global_load_lds_dwordx4 v184, s[12:13]
	s_waitcnt lgkmcnt(8)
	s_barrier
	s_waitcnt lgkmcnt(0)
	v_mfma_f32_16x16x32_f16 v[134:137], v[122:125], v[146:149], v[134:137]
	v_mfma_f32_16x16x32_f16 v[130:133], v[138:141], v[146:149], v[130:133]
	v_mfma_f32_16x16x32_f16 v[110:113], v[122:125], v[154:157], v[110:113]
	v_mfma_f32_16x16x32_f16 v[106:109], v[138:141], v[154:157], v[106:109]
	v_mfma_f32_16x16x32_f16 v[94:97], v[122:125], v[188:191], v[94:97]
	v_mfma_f32_16x16x32_f16 v[90:93], v[138:141], v[188:191], v[90:93]
	v_mfma_f32_16x16x32_f16 v[78:81], v[122:125], v[196:199], v[78:81]
	v_mfma_f32_16x16x32_f16 v[74:77], v[138:141], v[196:199], v[74:77]
	v_mfma_f32_16x16x32_f16 v[134:137], v[126:129], v[150:153], v[134:137]
	v_mfma_f32_16x16x32_f16 v[130:133], v[142:145], v[150:153], v[130:133]
	v_mfma_f32_16x16x32_f16 v[110:113], v[126:129], v[158:161], v[110:113]
	v_mfma_f32_16x16x32_f16 v[106:109], v[142:145], v[158:161], v[106:109]
	v_mfma_f32_16x16x32_f16 v[94:97], v[126:129], v[192:195], v[94:97]
	v_mfma_f32_16x16x32_f16 v[90:93], v[142:145], v[192:195], v[90:93]
	v_mfma_f32_16x16x32_f16 v[78:81], v[126:129], v[200:203], v[78:81]
	v_mfma_f32_16x16x32_f16 v[74:77], v[142:145], v[200:203], v[74:77]
	s_barrier
	ds_read_b128 v[212:215], v165 offset:16384
	ds_read_b128 v[234:237], v165 offset:17408
	ds_read_b128 v[238:241], v165 offset:18432
	ds_read_b128 v[242:245], v165 offset:19456
	v_add_u32_e32 v162, 0x80, v178
	s_add_i32 m0, s75, 0x10000
	s_nop 0
	global_load_lds_dwordx4 v178, s[48:49]
	s_add_i32 m0, s75, 0x12000
	s_nop 0
	global_load_lds_dwordx4 v174, s[48:49]
	s_barrier
	s_waitcnt lgkmcnt(0)
	v_mfma_f32_16x16x32_f16 v[118:121], v[212:215], v[146:149], v[118:121]
	v_mfma_f32_16x16x32_f16 v[114:117], v[238:241], v[146:149], v[114:117]
	v_mfma_f32_16x16x32_f16 v[102:105], v[212:215], v[154:157], v[102:105]
	v_mfma_f32_16x16x32_f16 v[98:101], v[238:241], v[154:157], v[98:101]
	v_mfma_f32_16x16x32_f16 v[86:89], v[212:215], v[188:191], v[86:89]
	v_mfma_f32_16x16x32_f16 v[82:85], v[238:241], v[188:191], v[82:85]
	v_mfma_f32_16x16x32_f16 v[70:73], v[212:215], v[196:199], v[70:73]
	v_mfma_f32_16x16x32_f16 v[66:69], v[238:241], v[196:199], v[66:69]
	v_mfma_f32_16x16x32_f16 v[118:121], v[234:237], v[150:153], v[118:121]
	v_mfma_f32_16x16x32_f16 v[114:117], v[242:245], v[150:153], v[114:117]
	v_mfma_f32_16x16x32_f16 v[102:105], v[234:237], v[158:161], v[102:105]
	v_mfma_f32_16x16x32_f16 v[98:101], v[242:245], v[158:161], v[98:101]
	v_mfma_f32_16x16x32_f16 v[86:89], v[234:237], v[192:195], v[86:89]
	v_mfma_f32_16x16x32_f16 v[82:85], v[242:245], v[192:195], v[82:85]
	v_mfma_f32_16x16x32_f16 v[70:73], v[234:237], v[200:203], v[70:73]
	v_mfma_f32_16x16x32_f16 v[66:69], v[242:245], v[200:203], v[66:69]
	s_mov_b32 m0, s71
	v_lshl_add_u64 v[170:171], s[50:51], 0, v[180:181]
	s_barrier
	ds_read_b128 v[146:149], v210 offset:16384
	ds_read_b128 v[150:153], v210 offset:17408
	ds_read_b128 v[154:157], v210 offset:18432
	ds_read_b128 v[158:161], v210 offset:19456
	ds_read_b128 v[188:191], v210 offset:20480
	ds_read_b128 v[192:195], v210 offset:21504
	ds_read_b128 v[196:199], v210 offset:22528
	ds_read_b128 v[200:203], v210 offset:23552
	global_load_lds_dwordx4 v[170:171], off
	v_lshl_add_u64 v[172:173], s[50:51], 0, v[176:177]
	s_mov_b32 m0, s61
	s_nop 0
	global_load_lds_dwordx4 v[172:173], off
	s_barrier
	s_waitcnt lgkmcnt(0)
	v_mfma_f32_16x16x32_f16 v[62:65], v[122:125], v[146:149], v[62:65]
	v_mfma_f32_16x16x32_f16 v[58:61], v[138:141], v[146:149], v[58:61]
	v_mfma_f32_16x16x32_f16 v[46:49], v[122:125], v[154:157], v[46:49]
	v_mfma_f32_16x16x32_f16 v[42:45], v[138:141], v[154:157], v[42:45]
	v_mfma_f32_16x16x32_f16 v[30:33], v[122:125], v[188:191], v[30:33]
	v_mfma_f32_16x16x32_f16 v[26:29], v[138:141], v[188:191], v[26:29]
	v_mfma_f32_16x16x32_f16 v[14:17], v[122:125], v[196:199], v[14:17]
	v_mfma_f32_16x16x32_f16 v[10:13], v[138:141], v[196:199], v[10:13]
	v_mfma_f32_16x16x32_f16 v[62:65], v[126:129], v[150:153], v[62:65]
	v_mfma_f32_16x16x32_f16 v[58:61], v[142:145], v[150:153], v[58:61]
	v_mfma_f32_16x16x32_f16 v[46:49], v[126:129], v[158:161], v[46:49]
	v_mfma_f32_16x16x32_f16 v[42:45], v[142:145], v[158:161], v[42:45]
	v_mfma_f32_16x16x32_f16 v[30:33], v[126:129], v[192:195], v[30:33]
	v_mfma_f32_16x16x32_f16 v[26:29], v[142:145], v[192:195], v[26:29]
	v_mfma_f32_16x16x32_f16 v[14:17], v[126:129], v[200:203], v[14:17]
	v_mfma_f32_16x16x32_f16 v[10:13], v[142:145], v[200:203], v[10:13]
	s_barrier
	s_add_u32 s90, s48, 0x80000
	s_addc_u32 s91, s49, 0
	s_add_i32 m0, s75, 0x14000
	s_nop 0
	global_load_lds_dwordx4 v178, s[90:91]
	s_add_i32 m0, s75, 0x16000
	s_nop 0
	global_load_lds_dwordx4 v174, s[90:91]
	s_waitcnt vmcnt(6)
	s_barrier
; #define PG8_STAGE(bufoff, gbase, voff) do { _Pragma("unroll") for (int _i = 0; _i < 2; ++_i) \
;         __builtin_amdgcn_global_load_lds((const unsigned*)((const char*)(gbase) + (voff)[_i]), (LAS unsigned*)(lds + (bufoff) + ldsw + _i * 8192), 16, 0, 0); } while (0)
; #define PG8_LDA(dst, b, h) do { _Pragma("unroll") for (int m = 0; m < 4; ++m) _Pragma("unroll") for (int k = 0; k < 2; ++k) dst[m][k] = *(const LAS f16x8*)(lds + PG8_SA(b, h) + aoff + m * 2048 + k * 1024); } while (0)
; #define PG8_LDB(dst, b, h) do { _Pragma("unroll") for (int n = 0; n < 2; ++n) _Pragma("unroll") for (int k = 0; k < 2; ++k) dst[n][k] = *(const LAS f16x8*)(lds + PG8_SB(b, h) + boff + n * 2048 + k * 1024); } while (0)
; #define PG8_MMA(ai, bj, At, Bt) do { __builtin_amdgcn_s_setprio(1); _Pragma("unroll") for (int m = 0; m < 4; ++m) _Pragma("unroll") for (int n = 0; n < 2; ++n) _Pragma("unroll") for (int k = 0; k < 2; ++k) \
;         acc[ai][bj][m][n] = __builtin_amdgcn_mfma_f32_16x16x32_f16(Bt[n][k], At[m][k], acc[ai][bj][m][n], 0, 0, 0); __builtin_amdgcn_s_setprio(0); } while (0)
; #define PG8_WAIT_V(n) asm volatile("s_waitcnt vmcnt(" #n ")" ::: "memory")
; #define PG8_WAIT_L(n) asm volatile("s_waitcnt lgkmcnt(" #n ")" ::: "memory")
; #define PG8_BAR __builtin_amdgcn_s_barrier()
; #define PG8_SCHED __builtin_amdgcn_sched_barrier(0)
; template <class Epi>
; __device__ __forceinline__ void gemm_phase(LAS unsigned char* lds, const Gemm g0, const StaticOrder& S, const Epi& E) {
;     ...
;             PG8_WAIT_V(6); PG8_BAR; PG8_MMA(1, 1, At, B1); PG8_BAR;
;             PG8_LDB(B0, 1, 0); PG8_SCHED; PG8_LDA(At, 1, 0); PG8_STAGE(PG8_SA(0, 1), a2 + hstep, voffA);
;             PG8_WAIT_L(8); PG8_BAR; PG8_WAIT_L(0); PG8_MMA(0, 0, At, B0); PG8_BAR; PG8_SCHED;
;             PG8_LDB(B1, 1, 1); PG8_STAGE(PG8_SB(1, 0), b3, voffB);
;             PG8_BAR; PG8_WAIT_L(0); PG8_MMA(0, 1, At, B1); PG8_BAR;
;             PG8_LDA(At, 1, 1); PG8_STAGE(PG8_SA(1, 0), a3, voffA);
	v_mfma_f32_16x16x32_f16 v[54:57], v[212:215], v[146:149], v[54:57]
	v_mfma_f32_16x16x32_f16 v[50:53], v[238:241], v[146:149], v[50:53]
	v_mfma_f32_16x16x32_f16 v[38:41], v[212:215], v[154:157], v[38:41]
	v_mfma_f32_16x16x32_f16 v[34:37], v[238:241], v[154:157], v[34:37]
	v_mfma_f32_16x16x32_f16 v[22:25], v[212:215], v[188:191], v[22:25]
	v_mfma_f32_16x16x32_f16 v[18:21], v[238:241], v[188:191], v[18:21]
	v_mfma_f32_16x16x32_f16 v[6:9], v[212:215], v[196:199], v[6:9]
	v_mfma_f32_16x16x32_f16 v[2:5], v[238:241], v[196:199], v[2:5]
	v_mfma_f32_16x16x32_f16 v[54:57], v[234:237], v[150:153], v[54:57]
	v_mfma_f32_16x16x32_f16 v[50:53], v[242:245], v[150:153], v[50:53]
	v_mfma_f32_16x16x32_f16 v[38:41], v[234:237], v[158:161], v[38:41]
	v_mfma_f32_16x16x32_f16 v[34:37], v[242:245], v[158:161], v[34:37]
	v_mfma_f32_16x16x32_f16 v[22:25], v[234:237], v[192:195], v[22:25]
	v_mfma_f32_16x16x32_f16 v[18:21], v[242:245], v[192:195], v[18:21]
	v_mfma_f32_16x16x32_f16 v[6:9], v[234:237], v[200:203], v[6:9]
	v_mfma_f32_16x16x32_f16 v[2:5], v[242:245], v[200:203], v[2:5]
	s_barrier
	ds_read_b128 v[122:125], v165 offset:32768
	ds_read_b128 v[126:129], v165 offset:33792
	ds_read_b128 v[138:141], v165 offset:34816
	ds_read_b128 v[142:145], v165 offset:35840
	s_add_u32 s50, s50, 0x80000
	s_addc_u32 s51, s51, 0
	s_mov_b32 m0, s74
	ds_read_b128 v[146:149], v210 offset:32768
	ds_read_b128 v[150:153], v210 offset:33792
	ds_read_b128 v[154:157], v210 offset:34816
	ds_read_b128 v[158:161], v210 offset:35840
	ds_read_b128 v[188:191], v210 offset:36864
	ds_read_b128 v[192:195], v210 offset:37888
	ds_read_b128 v[196:199], v210 offset:38912
	ds_read_b128 v[200:203], v210 offset:39936
	global_load_lds_dwordx4 v180, s[50:51]
	s_mov_b32 m0, s18
	s_nop 0
	global_load_lds_dwordx4 v176, s[50:51]
	s_waitcnt lgkmcnt(8)
	s_barrier
	s_waitcnt lgkmcnt(0)
	v_mfma_f32_16x16x32_f16 v[134:137], v[122:125], v[146:149], v[134:137]
	v_mfma_f32_16x16x32_f16 v[130:133], v[138:141], v[146:149], v[130:133]
	v_mfma_f32_16x16x32_f16 v[110:113], v[122:125], v[154:157], v[110:113]
	v_mfma_f32_16x16x32_f16 v[106:109], v[138:141], v[154:157], v[106:109]
	v_mfma_f32_16x16x32_f16 v[94:97], v[122:125], v[188:191], v[94:97]
	v_mfma_f32_16x16x32_f16 v[90:93], v[138:141], v[188:191], v[90:93]
	v_mfma_f32_16x16x32_f16 v[78:81], v[122:125], v[196:199], v[78:81]
	v_mfma_f32_16x16x32_f16 v[74:77], v[138:141], v[196:199], v[74:77]
	v_mfma_f32_16x16x32_f16 v[134:137], v[126:129], v[150:153], v[134:137]
	v_mfma_f32_16x16x32_f16 v[130:133], v[142:145], v[150:153], v[130:133]
	v_mfma_f32_16x16x32_f16 v[110:113], v[126:129], v[158:161], v[110:113]
	v_mfma_f32_16x16x32_f16 v[106:109], v[142:145], v[158:161], v[106:109]
	v_mfma_f32_16x16x32_f16 v[94:97], v[126:129], v[192:195], v[94:97]
	v_mfma_f32_16x16x32_f16 v[90:93], v[142:145], v[192:195], v[90:93]
	v_mfma_f32_16x16x32_f16 v[78:81], v[126:129], v[200:203], v[78:81]
	v_mfma_f32_16x16x32_f16 v[74:77], v[142:145], v[200:203], v[74:77]
	s_barrier
	s_add_i32 m0, s75, 0x18000
	ds_read_b128 v[212:215], v165 offset:49152
	ds_read_b128 v[234:237], v165 offset:50176
	ds_read_b128 v[238:241], v165 offset:51200
	ds_read_b128 v[242:245], v165 offset:52224
	global_load_lds_dwordx4 v162, s[48:49]
	s_add_i32 m0, s75, 0x1a000
	s_nop 0
	global_load_lds_dwordx4 v164, s[48:49]
	s_barrier
	s_waitcnt lgkmcnt(0)
	v_mfma_f32_16x16x32_f16 v[118:121], v[212:215], v[146:149], v[118:121]
	v_mfma_f32_16x16x32_f16 v[114:117], v[238:241], v[146:149], v[114:117]
	v_mfma_f32_16x16x32_f16 v[102:105], v[212:215], v[154:157], v[102:105]
	v_mfma_f32_16x16x32_f16 v[98:101], v[238:241], v[154:157], v[98:101]
	v_mfma_f32_16x16x32_f16 v[86:89], v[212:215], v[188:191], v[86:89]
	v_mfma_f32_16x16x32_f16 v[82:85], v[238:241], v[188:191], v[82:85]
	v_mfma_f32_16x16x32_f16 v[70:73], v[212:215], v[196:199], v[70:73]
	v_mfma_f32_16x16x32_f16 v[66:69], v[238:241], v[196:199], v[66:69]
	v_mfma_f32_16x16x32_f16 v[118:121], v[234:237], v[150:153], v[118:121]
	v_mfma_f32_16x16x32_f16 v[114:117], v[242:245], v[150:153], v[114:117]
	v_mfma_f32_16x16x32_f16 v[102:105], v[234:237], v[158:161], v[102:105]
	v_mfma_f32_16x16x32_f16 v[98:101], v[242:245], v[158:161], v[98:101]
	v_mfma_f32_16x16x32_f16 v[86:89], v[234:237], v[192:195], v[86:89]
	v_mfma_f32_16x16x32_f16 v[82:85], v[242:245], v[192:195], v[82:85]
	v_mfma_f32_16x16x32_f16 v[70:73], v[234:237], v[200:203], v[70:73]
	v_mfma_f32_16x16x32_f16 v[66:69], v[242:245], v[200:203], v[66:69]
	s_mov_b32 m0, s28
	v_lshl_add_u64 v[162:163], v[170:171], 0, s[64:65]
	s_barrier
; #define LAS __attribute__((address_space(3)))
; #define GAS __attribute__((address_space(1)))
;     __device__ __forceinline__ const float* resrow(int row, int colb) const { return (row < 8192 ? res0 + (size_t)row * DM : res1 + (size_t)(row - 8192) * DM) + colb; }
; #define PG8_STAGE(bufoff, gbase, voff) do { _Pragma("unroll") for (int _i = 0; _i < 2; ++_i) \
;         __builtin_amdgcn_global_load_lds((const unsigned*)((const char*)(gbase) + (voff)[_i]), (LAS unsigned*)(lds + (bufoff) + ldsw + _i * 8192), 16, 0, 0); } while (0)
; #define PG8_LDA(dst, b, h) do { _Pragma("unroll") for (int m = 0; m < 4; ++m) _Pragma("unroll") for (int k = 0; k < 2; ++k) dst[m][k] = *(const LAS f16x8*)(lds + PG8_SA(b, h) + aoff + m * 2048 + k * 1024); } while (0)
; #define PG8_WAIT_V(n) asm volatile("s_waitcnt vmcnt(" #n ")" ::: "memory")
; #define PG8_WAIT_L(n) asm volatile("s_waitcnt lgkmcnt(" #n ")" ::: "memory")
; #define PG8_BAR __builtin_amdgcn_s_barrier()
; #define PG8_SCHED __builtin_amdgcn_sched_barrier(0)
;     __device__ __forceinline__ void operator()(f32x4 (&acc)[2][2][4][2], const Unit& u, int wr, int wc, int fr, int fq) const {
;     ...
;         const bool hasln = pstats != nullptr, haszh = zh != nullptr;
;         LAS float* slot = vl + (wr * 4 + wc) * 256;
;         f32x4 rn[2][2]; float ssm[8], ssq[8]; f32x2 stn = {0.f, 0.f};
;         { const int lane = fr + 16 * fq, cL = u.pn * BM + wc * 32 + (lane < 32 ? lane : 96 + lane);
;           float vg = 0.f, vb = 0.f, vt = 0.f;
;           if (hasln) { vg = *(const GAS float*)(pg + cL); vb = *(const GAS float*)(pb + cL); }
;           if (haszh) vt = *(const GAS float*)(tg + cL);
;           const float* rp = resrow(row0, colb);
; #pragma unroll
;           for (int bj = 0; bj < 2; ++bj) { rn[bj][0] = ldg4(rp + bj * HALF); rn[bj][1] = ldg4(rp + bj * HALF + 4); }
;           if (hasln) stn = ldg2(pstats + 2 * (size_t)row0);
; template <class Epi>
; __device__ __forceinline__ void gemm_phase(LAS unsigned char* lds, const Gemm g0, const StaticOrder& S, const Epi& E) {
;     ...
;             PG8_LDA(At, 1, 1); PG8_STAGE(PG8_SA(1, 0), a3, voffA);
;             PG8_BAR; PG8_WAIT_L(0); PG8_MMA(1, 0, At, B0); PG8_BAR; PG8_SCHED;
;             PG8_STAGE(PG8_SB(1, 1), b3 + hstep, voffB);
;             PG8_WAIT_V(6); PG8_BAR; PG8_MMA(1, 1, At, B1); PG8_BAR;
;         }
	ds_read_b128 v[146:149], v210 offset:49152
	ds_read_b128 v[150:153], v210 offset:50176
	ds_read_b128 v[154:157], v210 offset:51200
	ds_read_b128 v[158:161], v210 offset:52224
	ds_read_b128 v[188:191], v210 offset:53248
	ds_read_b128 v[192:195], v210 offset:54272
	ds_read_b128 v[196:199], v210 offset:55296
	ds_read_b128 v[200:203], v210 offset:56320
	global_load_lds_dwordx4 v[162:163], off
	v_lshl_add_u64 v[162:163], v[172:173], 0, s[64:65]
	s_mov_b32 m0, s29
	s_nop 0
	global_load_lds_dwordx4 v[162:163], off
	s_barrier
	s_waitcnt lgkmcnt(0)
	v_mfma_f32_16x16x32_f16 v[62:65], v[122:125], v[146:149], v[62:65]
	v_mfma_f32_16x16x32_f16 v[58:61], v[138:141], v[146:149], v[58:61]
	v_mfma_f32_16x16x32_f16 v[46:49], v[122:125], v[154:157], v[46:49]
	v_mfma_f32_16x16x32_f16 v[42:45], v[138:141], v[154:157], v[42:45]
	v_mfma_f32_16x16x32_f16 v[30:33], v[122:125], v[188:191], v[30:33]
	v_mfma_f32_16x16x32_f16 v[26:29], v[138:141], v[188:191], v[26:29]
	v_mfma_f32_16x16x32_f16 v[14:17], v[122:125], v[196:199], v[14:17]
	v_mfma_f32_16x16x32_f16 v[10:13], v[138:141], v[196:199], v[10:13]
	v_mfma_f32_16x16x32_f16 v[62:65], v[126:129], v[150:153], v[62:65]
	v_mfma_f32_16x16x32_f16 v[58:61], v[142:145], v[150:153], v[58:61]
	v_mfma_f32_16x16x32_f16 v[46:49], v[126:129], v[158:161], v[46:49]
	v_mfma_f32_16x16x32_f16 v[42:45], v[142:145], v[158:161], v[42:45]
	v_mfma_f32_16x16x32_f16 v[30:33], v[126:129], v[192:195], v[30:33]
	v_mfma_f32_16x16x32_f16 v[26:29], v[142:145], v[192:195], v[26:29]
	v_mfma_f32_16x16x32_f16 v[14:17], v[126:129], v[200:203], v[14:17]
	v_mfma_f32_16x16x32_f16 v[10:13], v[142:145], v[200:203], v[10:13]
	s_barrier
	s_add_u32 s48, s48, 0x80080
	s_addc_u32 s49, s49, 0
	s_add_i32 m0, s75, 0x1c000
	s_nop 0
	global_load_lds_dwordx4 v178, s[48:49]
	s_add_i32 m0, s75, 0x1e000
	s_nop 0
	global_load_lds_dwordx4 v174, s[48:49]
	s_waitcnt vmcnt(6)
	s_barrier
	v_mfma_f32_16x16x32_f16 v[54:57], v[212:215], v[146:149], v[54:57]
	v_mfma_f32_16x16x32_f16 v[50:53], v[238:241], v[146:149], v[50:53]
	v_mfma_f32_16x16x32_f16 v[38:41], v[212:215], v[154:157], v[38:41]
	v_mfma_f32_16x16x32_f16 v[34:37], v[238:241], v[154:157], v[34:37]
	v_mfma_f32_16x16x32_f16 v[22:25], v[212:215], v[188:191], v[22:25]
	v_mfma_f32_16x16x32_f16 v[18:21], v[238:241], v[188:191], v[18:21]
	v_mfma_f32_16x16x32_f16 v[6:9], v[212:215], v[196:199], v[6:9]
	v_mfma_f32_16x16x32_f16 v[2:5], v[238:241], v[196:199], v[2:5]
	v_mfma_f32_16x16x32_f16 v[54:57], v[234:237], v[150:153], v[54:57]
	v_mfma_f32_16x16x32_f16 v[50:53], v[242:245], v[150:153], v[50:53]
	v_mfma_f32_16x16x32_f16 v[38:41], v[234:237], v[158:161], v[38:41]
	v_mfma_f32_16x16x32_f16 v[34:37], v[242:245], v[158:161], v[34:37]
	v_mfma_f32_16x16x32_f16 v[22:25], v[234:237], v[192:195], v[22:25]
	v_mfma_f32_16x16x32_f16 v[18:21], v[242:245], v[192:195], v[18:21]
	v_mfma_f32_16x16x32_f16 v[6:9], v[234:237], v[200:203], v[6:9]
	v_mfma_f32_16x16x32_f16 v[2:5], v[242:245], v[200:203], v[2:5]
	s_add_i32 s22, s22, 2
	s_add_u32 vcc_lo, vcc_lo, 0x100
	s_addc_u32 vcc_hi, vcc_hi, 0
	s_add_u32 s12, s12, 0x100
	s_addc_u32 s13, s13, 0
	s_cmp_gt_u32 s22, 29
	s_barrier
	s_cbranch_scc0 .LBB0_512
	s_lshl_b32 s12, s83, 8
	s_or_b32 s15, s12, s31
	v_add_u32_e32 v122, s15, v206
	v_cndmask_b32_e64 v124, 0, 1, s[44:45]
	v_ashrrev_i32_e32 v123, 31, v122
	v_mov_b32_e32 v196, 0
	v_cmp_ne_u32_e64 s[12:13], 1, v124
	s_andn2_b64 vcc, exec, s[44:45]
	v_mov_b32_e32 v124, 0
	v_mov_b32_e32 v125, 0
	s_cbranch_vccnz .LBB0_515
	v_lshlrev_b64 v[124:125], 2, v[122:123]
	v_lshl_add_u64 v[126:127], s[80:81], 0, v[124:125]
	v_lshl_add_u64 v[124:125], s[58:59], 0, v[124:125]
	global_load_dword v125, v[124:125], off
	s_nop 0
	global_load_dword v124, v[126:127], off

;     __device__ __forceinline__ void prefetch(const Unit& u, int wr, int wc, int lane) const { lnfold_prefetch(vl, stats, gW, bW, u, wr, wc, lane); }
;     __device__ __forceinline__ void prefetch(const Unit& u, int wr, int wc, int lane) const { lnfold_prefetch(vl, stats, gW, bW, u, wr, wc, lane); }
; #define PG8_STAGE(bufoff, gbase, voff) do { _Pragma("unroll") for (int _i = 0; _i < 2; ++_i) \
;         __builtin_amdgcn_global_load_lds((const unsigned*)((const char*)(gbase) + (voff)[_i]), (LAS unsigned*)(lds + (bufoff) + ldsw + _i * 8192), 16, 0, 0); } while (0)
; #define PG8_LDA(dst, b, h) do { _Pragma("unroll") for (int m = 0; m < 4; ++m) _Pragma("unroll") for (int k = 0; k < 2; ++k) dst[m][k] = *(const LAS f16x8*)(lds + PG8_SA(b, h) + aoff + m * 2048 + k * 1024); } while (0)
; #define PG8_LDB(dst, b, h) do { _Pragma("unroll") for (int n = 0; n < 2; ++n) _Pragma("unroll") for (int k = 0; k < 2; ++k) dst[n][k] = *(const LAS f16x8*)(lds + PG8_SB(b, h) + boff + n * 2048 + k * 1024); } while (0)
; #define PG8_WAIT_V(n) asm volatile("s_waitcnt vmcnt(" #n ")" ::: "memory")
; #define PG8_WAIT_L(n) asm volatile("s_waitcnt lgkmcnt(" #n ")" ::: "memory")
; #define PG8_BAR __builtin_amdgcn_s_barrier()
; template <class Epi>
; __device__ __forceinline__ void gemm_phase(LAS unsigned char* lds, const Gemm g0, const StaticOrder& S, const Epi& E) {
;     ...
;             const bool last = (t == nt - 2);
;             if (Epi::PREF && last) E.prefetch(cur, wr, wc, lane);
;             const char* a1 = cA + (size_t)(t + 1) * kstep;
;             const char* a2 = last ? nA : cA + (size_t)(t + 2) * kstep; const char* b2 = last ? nB : cB + (size_t)(t + 2) * kstep;
;             const char* a3 = a2 + kstep; const char* b3 = b2 + kstep;
;             PG8_LDB(B0, 0, 0); PG8_SCHED; PG8_LDA(At, 0, 0); PG8_STAGE(PG8_SA(1, 1), a1 + hstep, voffA);
;             PG8_WAIT_L(8); PG8_BAR; PG8_WAIT_L(0); PG8_MMA(0, 0, At, B0); PG8_BAR; PG8_SCHED;
;             PG8_LDB(B1, 0, 1); PG8_STAGE(PG8_SB(0, 0), b2, voffB);
;             PG8_BAR; PG8_WAIT_L(0); PG8_MMA(0, 1, At, B1); PG8_BAR;
;             PG8_LDA(At, 0, 1); PG8_STAGE(PG8_SA(0, 0), a2, voffA);
;             PG8_BAR; PG8_WAIT_L(0); PG8_MMA(1, 0, At, B0); PG8_BAR; PG8_SCHED;
;             PG8_STAGE(PG8_SB(0, 1), b2 + hstep, voffB);
;             PG8_WAIT_V(6); PG8_BAR; PG8_MMA(1, 1, At, B1); PG8_BAR;
.LBB0_620:
	s_add_u32 s58, s50, 0xfff80080
	s_addc_u32 s59, s51, -1
	s_and_b64 s[22:23], s[52:53], exec
	s_cselect_b32 s59, s37, s59
	s_cselect_b32 s58, s74, s58
	ds_read_b128 v[60:63], v187
	ds_read_b128 v[64:67], v187 offset:1024
	ds_read_b128 v[78:81], v187 offset:2048
	ds_read_b128 v[82:85], v187 offset:3072
	s_and_b64 s[22:23], s[52:53], exec
	s_cselect_b32 s53, s35, s25
	s_cselect_b32 s52, s75, s24
	s_add_i32 m0, s18, 0xc000
	ds_read_b128 v[86:89], v213
	ds_read_b128 v[90:93], v213 offset:1024
	ds_read_b128 v[194:197], v213 offset:2048
	ds_read_b128 v[234:237], v213 offset:3072
	ds_read_b128 v[238:241], v213 offset:4096
	ds_read_b128 v[242:245], v213 offset:5120
	ds_read_b128 v[246:249], v213 offset:6144
	ds_read_b128 v[226:229], v213 offset:7168
	global_load_lds_dwordx4 v184, s[50:51]
	s_add_i32 m0, s18, 0xe000
	s_nop 0
	global_load_lds_dwordx4 v182, s[50:51]
	s_waitcnt lgkmcnt(8)
	s_barrier
	s_waitcnt lgkmcnt(0)
	v_mfma_f32_16x16x32_f16 v[158:161], v[60:63], v[86:89], v[158:161]
	v_mfma_f32_16x16x32_f16 v[150:153], v[78:81], v[86:89], v[150:153]
	v_mfma_f32_16x16x32_f16 v[142:145], v[60:63], v[194:197], v[142:145]
	v_mfma_f32_16x16x32_f16 v[134:137], v[78:81], v[194:197], v[134:137]
	v_mfma_f32_16x16x32_f16 v[126:129], v[60:63], v[238:241], v[126:129]
	v_mfma_f32_16x16x32_f16 v[118:121], v[78:81], v[238:241], v[118:121]
	v_mfma_f32_16x16x32_f16 v[110:113], v[60:63], v[246:249], v[110:113]
	v_mfma_f32_16x16x32_f16 v[102:105], v[78:81], v[246:249], v[102:105]
	v_mfma_f32_16x16x32_f16 v[158:161], v[64:67], v[90:93], v[158:161]
	v_mfma_f32_16x16x32_f16 v[150:153], v[82:85], v[90:93], v[150:153]
	v_mfma_f32_16x16x32_f16 v[142:145], v[64:67], v[234:237], v[142:145]
	v_mfma_f32_16x16x32_f16 v[134:137], v[82:85], v[234:237], v[134:137]
	v_mfma_f32_16x16x32_f16 v[126:129], v[64:67], v[242:245], v[126:129]
	v_mfma_f32_16x16x32_f16 v[118:121], v[82:85], v[242:245], v[118:121]
	v_mfma_f32_16x16x32_f16 v[110:113], v[64:67], v[226:229], v[110:113]
	v_mfma_f32_16x16x32_f16 v[102:105], v[82:85], v[226:229], v[102:105]
	s_barrier
	s_add_i32 m0, s5, 0x10000
	ds_read_b128 v[162:165], v187 offset:16384
	ds_read_b128 v[222:225], v187 offset:17408
	ds_read_b128 v[214:217], v187 offset:18432
	ds_read_b128 v[170:173], v187 offset:19456
	global_load_lds_dwordx4 v178, s[52:53]
	s_add_i32 m0, s5, 0x12000
	s_nop 0
	global_load_lds_dwordx4 v174, s[52:53]
	s_barrier
	s_waitcnt lgkmcnt(0)
	v_mfma_f32_16x16x32_f16 v[154:157], v[162:165], v[86:89], v[154:157]
	v_mfma_f32_16x16x32_f16 v[86:89], v[214:217], v[86:89], v[146:149]
	v_mfma_f32_16x16x32_f16 v[130:133], v[214:217], v[194:197], v[130:133]
	v_mfma_f32_16x16x32_f16 v[122:125], v[162:165], v[238:241], v[122:125]
	v_mfma_f32_16x16x32_f16 v[114:117], v[214:217], v[238:241], v[114:117]
	v_mfma_f32_16x16x32_f16 v[106:109], v[162:165], v[246:249], v[106:109]
	v_mfma_f32_16x16x32_f16 v[98:101], v[214:217], v[246:249], v[98:101]
	v_mfma_f32_16x16x32_f16 v[154:157], v[222:225], v[90:93], v[154:157]
	v_mfma_f32_16x16x32_f16 v[86:89], v[170:173], v[90:93], v[86:89]
	v_mfma_f32_16x16x32_f16 v[90:93], v[162:165], v[194:197], v[138:141]
	v_mfma_f32_16x16x32_f16 v[130:133], v[170:173], v[234:237], v[130:133]
	v_mfma_f32_16x16x32_f16 v[122:125], v[222:225], v[242:245], v[122:125]
	v_mfma_f32_16x16x32_f16 v[114:117], v[170:173], v[242:245], v[114:117]
	v_mfma_f32_16x16x32_f16 v[106:109], v[222:225], v[226:229], v[106:109]
	v_mfma_f32_16x16x32_f16 v[98:101], v[170:173], v[226:229], v[98:101]
	v_mfma_f32_16x16x32_f16 v[90:93], v[222:225], v[234:237], v[90:93]
	s_mov_b32 m0, s18
	s_barrier
	ds_read_b128 v[138:141], v213 offset:16384
	ds_read_b128 v[146:149], v213 offset:17408
	ds_read_b128 v[194:197], v213 offset:18432
	ds_read_b128 v[226:229], v213 offset:19456
	ds_read_b128 v[234:237], v213 offset:20480
	ds_read_b128 v[238:241], v213 offset:21504
	ds_read_b128 v[242:245], v213 offset:22528
	ds_read_b128 v[246:249], v213 offset:23552
	global_load_lds_dwordx4 v180, s[58:59]
	s_mov_b32 m0, s19
	s_nop 0
	global_load_lds_dwordx4 v176, s[58:59]
	s_barrier
	s_waitcnt lgkmcnt(0)
	v_mfma_f32_16x16x32_f16 v[94:97], v[60:63], v[138:141], v[94:97]
	v_mfma_f32_16x16x32_f16 v[68:71], v[78:81], v[138:141], v[70:73]
	v_mfma_f32_16x16x32_f16 v[46:49], v[60:63], v[194:197], v[46:49]
	v_mfma_f32_16x16x32_f16 v[38:41], v[78:81], v[194:197], v[38:41]
	v_mfma_f32_16x16x32_f16 v[30:33], v[60:63], v[234:237], v[30:33]
	v_mfma_f32_16x16x32_f16 v[22:25], v[78:81], v[234:237], v[22:25]
	v_mfma_f32_16x16x32_f16 v[14:17], v[60:63], v[242:245], v[14:17]
	v_mfma_f32_16x16x32_f16 v[6:9], v[78:81], v[242:245], v[6:9]
	v_mfma_f32_16x16x32_f16 v[94:97], v[64:67], v[146:149], v[94:97]
	v_mfma_f32_16x16x32_f16 v[68:71], v[82:85], v[146:149], v[68:71]
	v_mfma_f32_16x16x32_f16 v[46:49], v[64:67], v[226:229], v[46:49]
	v_mfma_f32_16x16x32_f16 v[38:41], v[82:85], v[226:229], v[38:41]
	v_mfma_f32_16x16x32_f16 v[30:33], v[64:67], v[238:241], v[30:33]
	v_mfma_f32_16x16x32_f16 v[22:25], v[82:85], v[238:241], v[22:25]
	v_mfma_f32_16x16x32_f16 v[14:17], v[64:67], v[246:249], v[14:17]
	v_mfma_f32_16x16x32_f16 v[6:9], v[82:85], v[246:249], v[6:9]
	s_barrier
	s_add_u32 s22, s52, 0x80000
	s_addc_u32 s23, s53, 0
	s_add_i32 m0, s5, 0x14000
	s_nop 0
	global_load_lds_dwordx4 v178, s[22:23]
	s_add_i32 m0, s5, 0x16000
	s_nop 0
	global_load_lds_dwordx4 v174, s[22:23]
	s_waitcnt vmcnt(6)
	s_barrier
; #define PG8_STAGE(bufoff, gbase, voff) do { _Pragma("unroll") for (int _i = 0; _i < 2; ++_i) \
;         __builtin_amdgcn_global_load_lds((const unsigned*)((const char*)(gbase) + (voff)[_i]), (LAS unsigned*)(lds + (bufoff) + ldsw + _i * 8192), 16, 0, 0); } while (0)
; #define PG8_LDA(dst, b, h) do { _Pragma("unroll") for (int m = 0; m < 4; ++m) _Pragma("unroll") for (int k = 0; k < 2; ++k) dst[m][k] = *(const LAS f16x8*)(lds + PG8_SA(b, h) + aoff + m * 2048 + k * 1024); } while (0)
; #define PG8_LDB(dst, b, h) do { _Pragma("unroll") for (int n = 0; n < 2; ++n) _Pragma("unroll") for (int k = 0; k < 2; ++k) dst[n][k] = *(const LAS f16x8*)(lds + PG8_SB(b, h) + boff + n * 2048 + k * 1024); } while (0)
; #define PG8_MMA(ai, bj, At, Bt) do { __builtin_amdgcn_s_setprio(1); _Pragma("unroll") for (int m = 0; m < 4; ++m) _Pragma("unroll") for (int n = 0; n < 2; ++n) _Pragma("unroll") for (int k = 0; k < 2; ++k) \
;         acc[ai][bj][m][n] = __builtin_amdgcn_mfma_f32_16x16x32_f16(Bt[n][k], At[m][k], acc[ai][bj][m][n], 0, 0, 0); __builtin_amdgcn_s_setprio(0); } while (0)
; #define PG8_WAIT_V(n) asm volatile("s_waitcnt vmcnt(" #n ")" ::: "memory")
; #define PG8_WAIT_L(n) asm volatile("s_waitcnt lgkmcnt(" #n ")" ::: "memory")
; #define PG8_BAR __builtin_amdgcn_s_barrier()
; #define PG8_SCHED __builtin_amdgcn_sched_barrier(0)
; template <class Epi>
; __device__ __forceinline__ void gemm_phase(LAS unsigned char* lds, const Gemm g0, const StaticOrder& S, const Epi& E) {
;     ...
;             PG8_WAIT_V(6); PG8_BAR; PG8_MMA(1, 1, At, B1); PG8_BAR;
;             PG8_LDB(B0, 1, 0); PG8_SCHED; PG8_LDA(At, 1, 0); PG8_STAGE(PG8_SA(0, 1), a2 + hstep, voffA);
;             PG8_WAIT_L(8); PG8_BAR; PG8_WAIT_L(0); PG8_MMA(0, 0, At, B0); PG8_BAR; PG8_SCHED;
;             PG8_LDB(B1, 1, 1); PG8_STAGE(PG8_SB(1, 0), b3, voffB);
;             PG8_BAR; PG8_WAIT_L(0); PG8_MMA(0, 1, At, B1); PG8_BAR;
;             PG8_LDA(At, 1, 1); PG8_STAGE(PG8_SA(1, 0), a3, voffA);
;             PG8_BAR; PG8_WAIT_L(0); PG8_MMA(1, 0, At, B0); PG8_BAR; PG8_SCHED;
	v_mfma_f32_16x16x32_f16 v[50:53], v[214:217], v[138:141], v[50:53]
	v_mfma_f32_16x16x32_f16 v[42:45], v[162:165], v[194:197], v[42:45]
	v_mfma_f32_16x16x32_f16 v[34:37], v[214:217], v[194:197], v[34:37]
	v_mfma_f32_16x16x32_f16 v[26:29], v[162:165], v[234:237], v[26:29]
	v_mfma_f32_16x16x32_f16 v[18:21], v[214:217], v[234:237], v[18:21]
	v_mfma_f32_16x16x32_f16 v[10:13], v[162:165], v[242:245], v[10:13]
	v_mfma_f32_16x16x32_f16 v[2:5], v[214:217], v[242:245], v[2:5]
	v_mfma_f32_16x16x32_f16 v[60:63], v[162:165], v[138:141], v[74:77]
	v_mfma_f32_16x16x32_f16 v[50:53], v[170:173], v[146:149], v[50:53]
	v_mfma_f32_16x16x32_f16 v[42:45], v[222:225], v[226:229], v[42:45]
	v_mfma_f32_16x16x32_f16 v[34:37], v[170:173], v[226:229], v[34:37]
	v_mfma_f32_16x16x32_f16 v[26:29], v[222:225], v[238:241], v[26:29]
	v_mfma_f32_16x16x32_f16 v[18:21], v[170:173], v[238:241], v[18:21]
	v_mfma_f32_16x16x32_f16 v[10:13], v[222:225], v[246:249], v[10:13]
	v_mfma_f32_16x16x32_f16 v[2:5], v[170:173], v[246:249], v[2:5]
	v_mfma_f32_16x16x32_f16 v[60:63], v[222:225], v[146:149], v[60:63]
	s_barrier
	ds_read_b128 v[64:67], v187 offset:32768
	ds_read_b128 v[74:77], v187 offset:33792
	ds_read_b128 v[78:81], v187 offset:34816
	ds_read_b128 v[82:85], v187 offset:35840
	s_add_u32 s22, s58, 0x80000
	s_addc_u32 s23, s59, 0
	s_mov_b32 m0, s28
	ds_read_b128 v[138:141], v213 offset:32768
	ds_read_b128 v[146:149], v213 offset:33792
	ds_read_b128 v[162:165], v213 offset:34816
	ds_read_b128 v[170:173], v213 offset:35840
	ds_read_b128 v[194:197], v213 offset:36864
	ds_read_b128 v[214:217], v213 offset:37888
	ds_read_b128 v[222:225], v213 offset:38912
	ds_read_b128 v[226:229], v213 offset:39936
	global_load_lds_dwordx4 v180, s[22:23]
	s_mov_b32 m0, s29
	s_nop 0
	global_load_lds_dwordx4 v176, s[22:23]
	s_waitcnt lgkmcnt(8)
	s_barrier
	s_waitcnt lgkmcnt(0)
	v_mfma_f32_16x16x32_f16 v[158:161], v[64:67], v[138:141], v[158:161]
	v_mfma_f32_16x16x32_f16 v[150:153], v[78:81], v[138:141], v[150:153]
	v_mfma_f32_16x16x32_f16 v[142:145], v[64:67], v[162:165], v[142:145]
	v_mfma_f32_16x16x32_f16 v[134:137], v[78:81], v[162:165], v[134:137]
	v_mfma_f32_16x16x32_f16 v[126:129], v[64:67], v[194:197], v[126:129]
	v_mfma_f32_16x16x32_f16 v[118:121], v[78:81], v[194:197], v[118:121]
	v_mfma_f32_16x16x32_f16 v[110:113], v[64:67], v[222:225], v[110:113]
	v_mfma_f32_16x16x32_f16 v[102:105], v[78:81], v[222:225], v[102:105]
	v_mfma_f32_16x16x32_f16 v[158:161], v[74:77], v[146:149], v[158:161]
	v_mfma_f32_16x16x32_f16 v[150:153], v[82:85], v[146:149], v[150:153]
	v_mfma_f32_16x16x32_f16 v[142:145], v[74:77], v[170:173], v[142:145]
	v_mfma_f32_16x16x32_f16 v[134:137], v[82:85], v[170:173], v[134:137]
	v_mfma_f32_16x16x32_f16 v[126:129], v[74:77], v[214:217], v[126:129]
	v_mfma_f32_16x16x32_f16 v[118:121], v[82:85], v[214:217], v[118:121]
	v_mfma_f32_16x16x32_f16 v[110:113], v[74:77], v[226:229], v[110:113]
	v_mfma_f32_16x16x32_f16 v[102:105], v[82:85], v[226:229], v[102:105]
	s_barrier
	ds_read_b128 v[234:237], v187 offset:49152
	ds_read_b128 v[238:241], v187 offset:50176
	ds_read_b128 v[242:245], v187 offset:51200
	ds_read_b128 v[246:249], v187 offset:52224
	s_add_i32 m0, s5, 0x18000
	s_nop 0
	global_load_lds_dwordx4 v186, s[52:53]
	s_add_i32 m0, s5, 0x1a000
	s_nop 0
	global_load_lds_dwordx4 v190, s[52:53]
	s_barrier
; #define PG8_STAGE(bufoff, gbase, voff) do { _Pragma("unroll") for (int _i = 0; _i < 2; ++_i) \
;         __builtin_amdgcn_global_load_lds((const unsigned*)((const char*)(gbase) + (voff)[_i]), (LAS unsigned*)(lds + (bufoff) + ldsw + _i * 8192), 16, 0, 0); } while (0)
; #define PG8_MMA(ai, bj, At, Bt) do { __builtin_amdgcn_s_setprio(1); _Pragma("unroll") for (int m = 0; m < 4; ++m) _Pragma("unroll") for (int n = 0; n < 2; ++n) _Pragma("unroll") for (int k = 0; k < 2; ++k) \
;         acc[ai][bj][m][n] = __builtin_amdgcn_mfma_f32_16x16x32_f16(Bt[n][k], At[m][k], acc[ai][bj][m][n], 0, 0, 0); __builtin_amdgcn_s_setprio(0); } while (0)
; #define PG8_WAIT_V(n) asm volatile("s_waitcnt vmcnt(" #n ")" ::: "memory")
; #define PG8_WAIT_L(n) asm volatile("s_waitcnt lgkmcnt(" #n ")" ::: "memory")
; #define PG8_BAR __builtin_amdgcn_s_barrier()
; #define PG8_SCHED __builtin_amdgcn_sched_barrier(0)
; template <class Epi>
; __device__ __forceinline__ void gemm_phase(LAS unsigned char* lds, const Gemm g0, const StaticOrder& S, const Epi& E) {
;     ...
;             PG8_BAR; PG8_WAIT_L(0); PG8_MMA(1, 0, At, B0); PG8_BAR; PG8_SCHED;
;             PG8_STAGE(PG8_SB(1, 1), b3 + hstep, voffB);
;             PG8_WAIT_V(6); PG8_BAR; PG8_MMA(1, 1, At, B1); PG8_BAR;
;         }
	s_waitcnt lgkmcnt(0)
	v_mfma_f32_16x16x32_f16 v[154:157], v[234:237], v[138:141], v[154:157]
	v_mfma_f32_16x16x32_f16 v[86:89], v[242:245], v[138:141], v[86:89]
	v_mfma_f32_16x16x32_f16 v[154:157], v[238:241], v[146:149], v[154:157]
	v_mfma_f32_16x16x32_f16 v[146:149], v[246:249], v[146:149], v[86:89]
	v_mfma_f32_16x16x32_f16 v[86:89], v[234:237], v[162:165], v[90:93]
	v_mfma_f32_16x16x32_f16 v[138:141], v[238:241], v[170:173], v[86:89]
	v_mfma_f32_16x16x32_f16 v[86:89], v[242:245], v[162:165], v[130:133]
	v_mfma_f32_16x16x32_f16 v[130:133], v[246:249], v[170:173], v[86:89]
	v_mfma_f32_16x16x32_f16 v[86:89], v[234:237], v[194:197], v[122:125]
	v_mfma_f32_16x16x32_f16 v[122:125], v[238:241], v[214:217], v[86:89]
	v_mfma_f32_16x16x32_f16 v[86:89], v[242:245], v[194:197], v[114:117]
	v_mfma_f32_16x16x32_f16 v[114:117], v[246:249], v[214:217], v[86:89]
	v_mfma_f32_16x16x32_f16 v[86:89], v[234:237], v[222:225], v[106:109]
	v_mfma_f32_16x16x32_f16 v[106:109], v[238:241], v[226:229], v[86:89]
	v_mfma_f32_16x16x32_f16 v[86:89], v[242:245], v[222:225], v[98:101]
	v_mfma_f32_16x16x32_f16 v[98:101], v[246:249], v[226:229], v[86:89]
	s_mov_b32 m0, s31
	s_barrier
	s_nop 2
	ds_read_b128 v[86:89], v213 offset:49152
	ds_read_b128 v[90:93], v213 offset:50176
	ds_read_b128 v[162:165], v213 offset:51200
	ds_read_b128 v[170:173], v213 offset:52224
	ds_read_b128 v[194:197], v213 offset:53248
	ds_read_b128 v[214:217], v213 offset:54272
	ds_read_b128 v[222:225], v213 offset:55296
	ds_read_b128 v[226:229], v213 offset:56320
	global_load_lds_dwordx4 v198, s[58:59]
	s_mov_b32 m0, s61
	s_nop 0
	global_load_lds_dwordx4 v202, s[58:59]
	s_barrier
	s_waitcnt lgkmcnt(0)
	v_mfma_f32_16x16x32_f16 v[94:97], v[64:67], v[86:89], v[94:97]
	v_mfma_f32_16x16x32_f16 v[68:71], v[78:81], v[86:89], v[68:71]
	v_mfma_f32_16x16x32_f16 v[46:49], v[64:67], v[162:165], v[46:49]
	v_mfma_f32_16x16x32_f16 v[38:41], v[78:81], v[162:165], v[38:41]
	v_mfma_f32_16x16x32_f16 v[30:33], v[64:67], v[194:197], v[30:33]
	v_mfma_f32_16x16x32_f16 v[22:25], v[78:81], v[194:197], v[22:25]
	v_mfma_f32_16x16x32_f16 v[14:17], v[64:67], v[222:225], v[14:17]
	v_mfma_f32_16x16x32_f16 v[6:9], v[78:81], v[222:225], v[6:9]
	v_mfma_f32_16x16x32_f16 v[94:97], v[74:77], v[90:93], v[94:97]
	v_mfma_f32_16x16x32_f16 v[70:73], v[82:85], v[90:93], v[68:71]
	v_mfma_f32_16x16x32_f16 v[46:49], v[74:77], v[170:173], v[46:49]
	v_mfma_f32_16x16x32_f16 v[38:41], v[82:85], v[170:173], v[38:41]
	v_mfma_f32_16x16x32_f16 v[30:33], v[74:77], v[214:217], v[30:33]
	v_mfma_f32_16x16x32_f16 v[22:25], v[82:85], v[214:217], v[22:25]
	v_mfma_f32_16x16x32_f16 v[14:17], v[74:77], v[226:229], v[14:17]
	v_mfma_f32_16x16x32_f16 v[6:9], v[82:85], v[226:229], v[6:9]
	s_barrier
	s_add_u32 s22, s52, 0x80080
	s_addc_u32 s23, s53, 0
	s_add_i32 m0, s5, 0x1c000
	s_nop 0
	global_load_lds_dwordx4 v178, s[22:23]
	s_add_i32 m0, s5, 0x1e000
	s_nop 0
	global_load_lds_dwordx4 v174, s[22:23]
	s_waitcnt vmcnt(6)
	s_barrier
	v_mfma_f32_16x16x32_f16 v[60:63], v[234:237], v[86:89], v[60:63]
	v_mfma_f32_16x16x32_f16 v[50:53], v[242:245], v[86:89], v[50:53]
	v_mfma_f32_16x16x32_f16 v[42:45], v[234:237], v[162:165], v[42:45]
	v_mfma_f32_16x16x32_f16 v[34:37], v[242:245], v[162:165], v[34:37]
	v_mfma_f32_16x16x32_f16 v[26:29], v[234:237], v[194:197], v[26:29]
	v_mfma_f32_16x16x32_f16 v[18:21], v[242:245], v[194:197], v[18:21]
	v_mfma_f32_16x16x32_f16 v[10:13], v[234:237], v[222:225], v[10:13]
	v_mfma_f32_16x16x32_f16 v[2:5], v[242:245], v[222:225], v[2:5]
	v_mfma_f32_16x16x32_f16 v[74:77], v[238:241], v[90:93], v[60:63]
	v_mfma_f32_16x16x32_f16 v[50:53], v[246:249], v[90:93], v[50:53]
	v_mfma_f32_16x16x32_f16 v[42:45], v[238:241], v[170:173], v[42:45]
	v_mfma_f32_16x16x32_f16 v[34:37], v[246:249], v[170:173], v[34:37]
	v_mfma_f32_16x16x32_f16 v[26:29], v[238:241], v[214:217], v[26:29]
	v_mfma_f32_16x16x32_f16 v[18:21], v[246:249], v[214:217], v[18:21]
	v_mfma_f32_16x16x32_f16 v[10:13], v[238:241], v[226:229], v[10:13]
	v_mfma_f32_16x16x32_f16 v[2:5], v[246:249], v[226:229], v[2:5]
	s_add_i32 s81, s81, 2
	s_add_u32 s24, s24, 0x100
	s_addc_u32 s25, s25, 0
	s_add_u32 s50, s50, 0x100
	s_addc_u32 s51, s51, 0
	s_cmp_gt_u32 s81, 29
	s_barrier
	s_cbranch_scc1 .LBB0_616

;     __device__ __forceinline__ void prefetch(const Unit& u, int wr, int wc, int lane) const { lnfold_prefetch(vl, stats, gW, bW, u, wr, wc, lane); }
;     __device__ __forceinline__ void prefetch(const Unit& u, int wr, int wc, int lane) const { lnfold_prefetch(vl, stats, gW, bW, u, wr, wc, lane); }
; #define PG8_STAGE(bufoff, gbase, voff) do { _Pragma("unroll") for (int _i = 0; _i < 2; ++_i) \
;         __builtin_amdgcn_global_load_lds((const unsigned*)((const char*)(gbase) + (voff)[_i]), (LAS unsigned*)(lds + (bufoff) + ldsw + _i * 8192), 16, 0, 0); } while (0)
; #define PG8_LDA(dst, b, h) do { _Pragma("unroll") for (int m = 0; m < 4; ++m) _Pragma("unroll") for (int k = 0; k < 2; ++k) dst[m][k] = *(const LAS f16x8*)(lds + PG8_SA(b, h) + aoff + m * 2048 + k * 1024); } while (0)
; #define PG8_LDB(dst, b, h) do { _Pragma("unroll") for (int n = 0; n < 2; ++n) _Pragma("unroll") for (int k = 0; k < 2; ++k) dst[n][k] = *(const LAS f16x8*)(lds + PG8_SB(b, h) + boff + n * 2048 + k * 1024); } while (0)
; #define PG8_WAIT_V(n) asm volatile("s_waitcnt vmcnt(" #n ")" ::: "memory")
; #define PG8_WAIT_L(n) asm volatile("s_waitcnt lgkmcnt(" #n ")" ::: "memory")
; #define PG8_BAR __builtin_amdgcn_s_barrier()
; template <class Epi>
; __device__ __forceinline__ void gemm_phase(LAS unsigned char* lds, const Gemm g0, const StaticOrder& S, const Epi& E) {
;     ...
;             const bool last = (t == nt - 2);
;             if (Epi::PREF && last) E.prefetch(cur, wr, wc, lane);
;             const char* a1 = cA + (size_t)(t + 1) * kstep;
;             const char* a2 = last ? nA : cA + (size_t)(t + 2) * kstep; const char* b2 = last ? nB : cB + (size_t)(t + 2) * kstep;
;             const char* a3 = a2 + kstep; const char* b3 = b2 + kstep;
;             PG8_LDB(B0, 0, 0); PG8_SCHED; PG8_LDA(At, 0, 0); PG8_STAGE(PG8_SA(1, 1), a1 + hstep, voffA);
;             PG8_WAIT_L(8); PG8_BAR; PG8_WAIT_L(0); PG8_MMA(0, 0, At, B0); PG8_BAR; PG8_SCHED;
;             PG8_LDB(B1, 0, 1); PG8_STAGE(PG8_SB(0, 0), b2, voffB);
;             PG8_BAR; PG8_WAIT_L(0); PG8_MMA(0, 1, At, B1); PG8_BAR;
;             PG8_LDA(At, 0, 1); PG8_STAGE(PG8_SA(0, 0), a2, voffA);
;             PG8_BAR; PG8_WAIT_L(0); PG8_MMA(1, 0, At, B0); PG8_BAR; PG8_SCHED;
;             PG8_STAGE(PG8_SB(0, 1), b2 + hstep, voffB);
;             PG8_WAIT_V(6); PG8_BAR; PG8_MMA(1, 1, At, B1); PG8_BAR;
.LBB0_672:
	s_add_u32 s10, s12, 0x100
	s_addc_u32 s11, s13, 0
	ds_read_b128 v[130:133], v201
	ds_read_b128 v[134:137], v201 offset:1024
	ds_read_b128 v[138:141], v201 offset:2048
	ds_read_b128 v[142:145], v201 offset:3072
	s_cmpk_eq_i32 s22, 0x54
	s_cselect_b32 s81, s1, s11
	s_cselect_b32 s80, s0, s10
	s_cselect_b32 s63, s59, s25
	s_cselect_b32 s62, s58, s24
	s_add_i32 m0, s28, 0xc000
	ds_read_b128 v[146:149], v208
	ds_read_b128 v[150:153], v208 offset:1024
	ds_read_b128 v[154:157], v208 offset:2048
	ds_read_b128 v[162:165], v208 offset:3072
	ds_read_b128 v[170:173], v208 offset:4096
	ds_read_b128 v[184:187], v208 offset:5120
	ds_read_b128 v[188:191], v208 offset:6144
	ds_read_b128 v[192:195], v208 offset:7168
	global_load_lds_dwordx4 v182, s[12:13]
	s_add_i32 m0, s28, 0xe000
	s_nop 0
	global_load_lds_dwordx4 v180, s[12:13]
	s_waitcnt lgkmcnt(8)
	s_barrier
	s_waitcnt lgkmcnt(0)
	v_mfma_f32_16x16x32_f16 v[126:129], v[130:133], v[146:149], v[126:129]
	v_mfma_f32_16x16x32_f16 v[122:125], v[138:141], v[146:149], v[122:125]
	v_mfma_f32_16x16x32_f16 v[110:113], v[130:133], v[154:157], v[110:113]
	v_mfma_f32_16x16x32_f16 v[106:109], v[138:141], v[154:157], v[106:109]
	v_mfma_f32_16x16x32_f16 v[94:97], v[130:133], v[170:173], v[94:97]
	v_mfma_f32_16x16x32_f16 v[90:93], v[138:141], v[170:173], v[90:93]
	v_mfma_f32_16x16x32_f16 v[78:81], v[130:133], v[188:191], v[78:81]
	v_mfma_f32_16x16x32_f16 v[74:77], v[138:141], v[188:191], v[74:77]
	v_mfma_f32_16x16x32_f16 v[126:129], v[134:137], v[150:153], v[126:129]
	v_mfma_f32_16x16x32_f16 v[122:125], v[142:145], v[150:153], v[122:125]
	v_mfma_f32_16x16x32_f16 v[110:113], v[134:137], v[162:165], v[110:113]
	v_mfma_f32_16x16x32_f16 v[106:109], v[142:145], v[162:165], v[106:109]
	v_mfma_f32_16x16x32_f16 v[94:97], v[134:137], v[184:187], v[94:97]
	v_mfma_f32_16x16x32_f16 v[90:93], v[142:145], v[184:187], v[90:93]
	v_mfma_f32_16x16x32_f16 v[78:81], v[134:137], v[192:195], v[78:81]
	v_mfma_f32_16x16x32_f16 v[74:77], v[142:145], v[192:195], v[74:77]
	s_barrier
	ds_read_b128 v[196:199], v201 offset:16384
	ds_read_b128 v[210:213], v201 offset:17408
	ds_read_b128 v[214:217], v201 offset:18432
	s_add_i32 m0, s19, 0x10000
	ds_read_b128 v[222:225], v201 offset:19456
	global_load_lds_dwordx4 v174, s[62:63]
	s_add_i32 m0, s19, 0x12000
	s_nop 0
	global_load_lds_dwordx4 v158, s[62:63]
	s_barrier
	s_waitcnt lgkmcnt(0)
	v_mfma_f32_16x16x32_f16 v[118:121], v[196:199], v[146:149], v[118:121]
	v_mfma_f32_16x16x32_f16 v[114:117], v[214:217], v[146:149], v[114:117]
	v_mfma_f32_16x16x32_f16 v[102:105], v[196:199], v[154:157], v[102:105]
	v_mfma_f32_16x16x32_f16 v[98:101], v[214:217], v[154:157], v[98:101]
	v_mfma_f32_16x16x32_f16 v[86:89], v[196:199], v[170:173], v[86:89]
	v_mfma_f32_16x16x32_f16 v[82:85], v[214:217], v[170:173], v[82:85]
	v_mfma_f32_16x16x32_f16 v[70:73], v[196:199], v[188:191], v[70:73]
	v_mfma_f32_16x16x32_f16 v[66:69], v[214:217], v[188:191], v[66:69]
	v_mfma_f32_16x16x32_f16 v[118:121], v[210:213], v[150:153], v[118:121]
	v_mfma_f32_16x16x32_f16 v[114:117], v[222:225], v[150:153], v[114:117]
	v_mfma_f32_16x16x32_f16 v[102:105], v[210:213], v[162:165], v[102:105]
	v_mfma_f32_16x16x32_f16 v[98:101], v[222:225], v[162:165], v[98:101]
	v_mfma_f32_16x16x32_f16 v[86:89], v[210:213], v[184:187], v[86:89]
	v_mfma_f32_16x16x32_f16 v[82:85], v[222:225], v[184:187], v[82:85]
	v_mfma_f32_16x16x32_f16 v[70:73], v[210:213], v[192:195], v[70:73]
	v_mfma_f32_16x16x32_f16 v[66:69], v[222:225], v[192:195], v[66:69]
	s_mov_b32 m0, s28
	s_barrier
	ds_read_b128 v[146:149], v208 offset:16384
	ds_read_b128 v[150:153], v208 offset:17408
	ds_read_b128 v[154:157], v208 offset:18432
	ds_read_b128 v[162:165], v208 offset:19456
	ds_read_b128 v[170:173], v208 offset:20480
	ds_read_b128 v[184:187], v208 offset:21504
	ds_read_b128 v[188:191], v208 offset:22528
	ds_read_b128 v[192:195], v208 offset:23552
	global_load_lds_dwordx4 v176, s[80:81]
	s_mov_b32 m0, s29
	s_nop 0
	global_load_lds_dwordx4 v160, s[80:81]
	s_barrier
	s_waitcnt lgkmcnt(0)
	v_mfma_f32_16x16x32_f16 v[62:65], v[130:133], v[146:149], v[62:65]
	v_mfma_f32_16x16x32_f16 v[58:61], v[138:141], v[146:149], v[58:61]
	v_mfma_f32_16x16x32_f16 v[46:49], v[130:133], v[154:157], v[46:49]
	v_mfma_f32_16x16x32_f16 v[42:45], v[138:141], v[154:157], v[42:45]
	v_mfma_f32_16x16x32_f16 v[30:33], v[130:133], v[170:173], v[30:33]
	v_mfma_f32_16x16x32_f16 v[26:29], v[138:141], v[170:173], v[26:29]
	v_mfma_f32_16x16x32_f16 v[14:17], v[130:133], v[188:191], v[14:17]
	v_mfma_f32_16x16x32_f16 v[10:13], v[138:141], v[188:191], v[10:13]
	v_mfma_f32_16x16x32_f16 v[62:65], v[134:137], v[150:153], v[62:65]
	v_mfma_f32_16x16x32_f16 v[58:61], v[142:145], v[150:153], v[58:61]
	v_mfma_f32_16x16x32_f16 v[46:49], v[134:137], v[162:165], v[46:49]
	v_mfma_f32_16x16x32_f16 v[42:45], v[142:145], v[162:165], v[42:45]
	v_mfma_f32_16x16x32_f16 v[30:33], v[134:137], v[184:187], v[30:33]
	v_mfma_f32_16x16x32_f16 v[26:29], v[142:145], v[184:187], v[26:29]
	v_mfma_f32_16x16x32_f16 v[14:17], v[134:137], v[192:195], v[14:17]
	v_mfma_f32_16x16x32_f16 v[10:13], v[142:145], v[192:195], v[10:13]
	s_barrier
	s_add_u32 s12, s62, 0x160000
	s_addc_u32 s13, s63, 0
	s_add_i32 m0, s19, 0x14000
	s_nop 0
	global_load_lds_dwordx4 v174, s[12:13]
	s_add_i32 m0, s19, 0x16000
	s_nop 0
	global_load_lds_dwordx4 v158, s[12:13]
	s_waitcnt vmcnt(6)
	s_barrier
; #define PG8_STAGE(bufoff, gbase, voff) do { _Pragma("unroll") for (int _i = 0; _i < 2; ++_i) \
;         __builtin_amdgcn_global_load_lds((const unsigned*)((const char*)(gbase) + (voff)[_i]), (LAS unsigned*)(lds + (bufoff) + ldsw + _i * 8192), 16, 0, 0); } while (0)
; #define PG8_LDA(dst, b, h) do { _Pragma("unroll") for (int m = 0; m < 4; ++m) _Pragma("unroll") for (int k = 0; k < 2; ++k) dst[m][k] = *(const LAS f16x8*)(lds + PG8_SA(b, h) + aoff + m * 2048 + k * 1024); } while (0)
; #define PG8_LDB(dst, b, h) do { _Pragma("unroll") for (int n = 0; n < 2; ++n) _Pragma("unroll") for (int k = 0; k < 2; ++k) dst[n][k] = *(const LAS f16x8*)(lds + PG8_SB(b, h) + boff + n * 2048 + k * 1024); } while (0)
; #define PG8_MMA(ai, bj, At, Bt) do { __builtin_amdgcn_s_setprio(1); _Pragma("unroll") for (int m = 0; m < 4; ++m) _Pragma("unroll") for (int n = 0; n < 2; ++n) _Pragma("unroll") for (int k = 0; k < 2; ++k) \
;         acc[ai][bj][m][n] = __builtin_amdgcn_mfma_f32_16x16x32_f16(Bt[n][k], At[m][k], acc[ai][bj][m][n], 0, 0, 0); __builtin_amdgcn_s_setprio(0); } while (0)
; #define PG8_WAIT_V(n) asm volatile("s_waitcnt vmcnt(" #n ")" ::: "memory")
; #define PG8_WAIT_L(n) asm volatile("s_waitcnt lgkmcnt(" #n ")" ::: "memory")
; #define PG8_BAR __builtin_amdgcn_s_barrier()
; #define PG8_SCHED __builtin_amdgcn_sched_barrier(0)
; template <class Epi>
; __device__ __forceinline__ void gemm_phase(LAS unsigned char* lds, const Gemm g0, const StaticOrder& S, const Epi& E) {
;     ...
;             PG8_WAIT_V(6); PG8_BAR; PG8_MMA(1, 1, At, B1); PG8_BAR;
;             PG8_LDB(B0, 1, 0); PG8_SCHED; PG8_LDA(At, 1, 0); PG8_STAGE(PG8_SA(0, 1), a2 + hstep, voffA);
;             PG8_WAIT_L(8); PG8_BAR; PG8_WAIT_L(0); PG8_MMA(0, 0, At, B0); PG8_BAR; PG8_SCHED;
;             PG8_LDB(B1, 1, 1); PG8_STAGE(PG8_SB(1, 0), b3, voffB);
;             PG8_BAR; PG8_WAIT_L(0); PG8_MMA(0, 1, At, B1); PG8_BAR;
;             PG8_LDA(At, 1, 1); PG8_STAGE(PG8_SA(1, 0), a3, voffA);
	v_mfma_f32_16x16x32_f16 v[54:57], v[196:199], v[146:149], v[54:57]
	v_mfma_f32_16x16x32_f16 v[50:53], v[214:217], v[146:149], v[50:53]
	v_mfma_f32_16x16x32_f16 v[38:41], v[196:199], v[154:157], v[38:41]
	v_mfma_f32_16x16x32_f16 v[34:37], v[214:217], v[154:157], v[34:37]
	v_mfma_f32_16x16x32_f16 v[22:25], v[196:199], v[170:173], v[22:25]
	v_mfma_f32_16x16x32_f16 v[18:21], v[214:217], v[170:173], v[18:21]
	v_mfma_f32_16x16x32_f16 v[6:9], v[196:199], v[188:191], v[6:9]
	v_mfma_f32_16x16x32_f16 v[2:5], v[214:217], v[188:191], v[2:5]
	v_mfma_f32_16x16x32_f16 v[54:57], v[210:213], v[150:153], v[54:57]
	v_mfma_f32_16x16x32_f16 v[50:53], v[222:225], v[150:153], v[50:53]
	v_mfma_f32_16x16x32_f16 v[38:41], v[210:213], v[162:165], v[38:41]
	v_mfma_f32_16x16x32_f16 v[34:37], v[222:225], v[162:165], v[34:37]
	v_mfma_f32_16x16x32_f16 v[22:25], v[210:213], v[184:187], v[22:25]
	v_mfma_f32_16x16x32_f16 v[18:21], v[222:225], v[184:187], v[18:21]
	v_mfma_f32_16x16x32_f16 v[6:9], v[210:213], v[192:195], v[6:9]
	v_mfma_f32_16x16x32_f16 v[2:5], v[222:225], v[192:195], v[2:5]
	s_barrier
	ds_read_b128 v[130:133], v201 offset:32768
	ds_read_b128 v[134:137], v201 offset:33792
	ds_read_b128 v[138:141], v201 offset:34816
	ds_read_b128 v[142:145], v201 offset:35840
	s_add_u32 s12, s80, 0x160000
	s_addc_u32 s13, s81, 0
	s_mov_b32 m0, s31
	ds_read_b128 v[146:149], v208 offset:32768
	ds_read_b128 v[150:153], v208 offset:33792
	ds_read_b128 v[154:157], v208 offset:34816
	ds_read_b128 v[162:165], v208 offset:35840
	ds_read_b128 v[170:173], v208 offset:36864
	ds_read_b128 v[184:187], v208 offset:37888
	ds_read_b128 v[188:191], v208 offset:38912
	ds_read_b128 v[192:195], v208 offset:39936
	global_load_lds_dwordx4 v176, s[12:13]
	s_mov_b32 m0, s61
	s_nop 0
	global_load_lds_dwordx4 v160, s[12:13]
	s_waitcnt lgkmcnt(8)
	s_barrier
	s_waitcnt lgkmcnt(0)
	v_mfma_f32_16x16x32_f16 v[126:129], v[130:133], v[146:149], v[126:129]
	v_mfma_f32_16x16x32_f16 v[122:125], v[138:141], v[146:149], v[122:125]
	v_mfma_f32_16x16x32_f16 v[110:113], v[130:133], v[154:157], v[110:113]
	v_mfma_f32_16x16x32_f16 v[106:109], v[138:141], v[154:157], v[106:109]
	v_mfma_f32_16x16x32_f16 v[94:97], v[130:133], v[170:173], v[94:97]
	v_mfma_f32_16x16x32_f16 v[90:93], v[138:141], v[170:173], v[90:93]
	v_mfma_f32_16x16x32_f16 v[78:81], v[130:133], v[188:191], v[78:81]
	v_mfma_f32_16x16x32_f16 v[74:77], v[138:141], v[188:191], v[74:77]
	v_mfma_f32_16x16x32_f16 v[126:129], v[134:137], v[150:153], v[126:129]
	v_mfma_f32_16x16x32_f16 v[122:125], v[142:145], v[150:153], v[122:125]
	v_mfma_f32_16x16x32_f16 v[110:113], v[134:137], v[162:165], v[110:113]
	v_mfma_f32_16x16x32_f16 v[106:109], v[142:145], v[162:165], v[106:109]
	v_mfma_f32_16x16x32_f16 v[94:97], v[134:137], v[184:187], v[94:97]
	v_mfma_f32_16x16x32_f16 v[90:93], v[142:145], v[184:187], v[90:93]
	v_mfma_f32_16x16x32_f16 v[78:81], v[134:137], v[192:195], v[78:81]
	v_mfma_f32_16x16x32_f16 v[74:77], v[142:145], v[192:195], v[74:77]
	s_barrier
	s_add_i32 m0, s19, 0x18000
	ds_read_b128 v[196:199], v201 offset:49152
	ds_read_b128 v[210:213], v201 offset:50176
	ds_read_b128 v[214:217], v201 offset:51200
	ds_read_b128 v[222:225], v201 offset:52224
	global_load_lds_dwordx4 v200, s[62:63]
	s_add_i32 m0, s19, 0x1a000
	s_nop 0
	global_load_lds_dwordx4 v218, s[62:63]
	s_barrier
	s_waitcnt lgkmcnt(0)
	v_mfma_f32_16x16x32_f16 v[118:121], v[196:199], v[146:149], v[118:121]
	v_mfma_f32_16x16x32_f16 v[114:117], v[214:217], v[146:149], v[114:117]
	v_mfma_f32_16x16x32_f16 v[102:105], v[196:199], v[154:157], v[102:105]
	v_mfma_f32_16x16x32_f16 v[98:101], v[214:217], v[154:157], v[98:101]
	v_mfma_f32_16x16x32_f16 v[86:89], v[196:199], v[170:173], v[86:89]
	v_mfma_f32_16x16x32_f16 v[82:85], v[214:217], v[170:173], v[82:85]
	v_mfma_f32_16x16x32_f16 v[70:73], v[196:199], v[188:191], v[70:73]
	v_mfma_f32_16x16x32_f16 v[66:69], v[214:217], v[188:191], v[66:69]
	v_mfma_f32_16x16x32_f16 v[118:121], v[210:213], v[150:153], v[118:121]
	v_mfma_f32_16x16x32_f16 v[114:117], v[222:225], v[150:153], v[114:117]
	v_mfma_f32_16x16x32_f16 v[102:105], v[210:213], v[162:165], v[102:105]
	v_mfma_f32_16x16x32_f16 v[98:101], v[222:225], v[162:165], v[98:101]
	v_mfma_f32_16x16x32_f16 v[86:89], v[210:213], v[184:187], v[86:89]
	v_mfma_f32_16x16x32_f16 v[82:85], v[222:225], v[184:187], v[82:85]
	v_mfma_f32_16x16x32_f16 v[70:73], v[210:213], v[192:195], v[70:73]
	v_mfma_f32_16x16x32_f16 v[66:69], v[222:225], v[192:195], v[66:69]
	s_mov_b32 m0, s83
	s_barrier
; #define LAS __attribute__((address_space(3)))
; #define GAS __attribute__((address_space(1)))
;     __device__ __forceinline__ const float* resrow(int row, int colb) const { return (row < 8192 ? res0 + (size_t)row * DM : res1 + (size_t)(row - 8192) * DM) + colb; }
; #define PG8_STAGE(bufoff, gbase, voff) do { _Pragma("unroll") for (int _i = 0; _i < 2; ++_i) \
;         __builtin_amdgcn_global_load_lds((const unsigned*)((const char*)(gbase) + (voff)[_i]), (LAS unsigned*)(lds + (bufoff) + ldsw + _i * 8192), 16, 0, 0); } while (0)
; #define PG8_LDA(dst, b, h) do { _Pragma("unroll") for (int m = 0; m < 4; ++m) _Pragma("unroll") for (int k = 0; k < 2; ++k) dst[m][k] = *(const LAS f16x8*)(lds + PG8_SA(b, h) + aoff + m * 2048 + k * 1024); } while (0)
; #define PG8_WAIT_V(n) asm volatile("s_waitcnt vmcnt(" #n ")" ::: "memory")
; #define PG8_WAIT_L(n) asm volatile("s_waitcnt lgkmcnt(" #n ")" ::: "memory")
; #define PG8_BAR __builtin_amdgcn_s_barrier()
; #define PG8_SCHED __builtin_amdgcn_sched_barrier(0)
;     __device__ __forceinline__ void operator()(f32x4 (&acc)[2][2][4][2], const Unit& u, int wr, int wc, int fr, int fq) const {
;     ...
;         const bool hasln = pstats != nullptr, haszh = zh != nullptr;
;         LAS float* slot = vl + (wr * 4 + wc) * 256;
;         f32x4 rn[2][2]; float ssm[8], ssq[8]; f32x2 stn = {0.f, 0.f};
;         { const int lane = fr + 16 * fq, cL = u.pn * BM + wc * 32 + (lane < 32 ? lane : 96 + lane);
;           float vg = 0.f, vb = 0.f, vt = 0.f;
;           if (hasln) { vg = *(const GAS float*)(pg + cL); vb = *(const GAS float*)(pb + cL); }
;           if (haszh) vt = *(const GAS float*)(tg + cL);
;           const float* rp = resrow(row0, colb);
; #pragma unroll
;           for (int bj = 0; bj < 2; ++bj) { rn[bj][0] = ldg4(rp + bj * HALF); rn[bj][1] = ldg4(rp + bj * HALF + 4); }
;           if (hasln) stn = ldg2(pstats + 2 * (size_t)row0);
; template <class Epi>
; __device__ __forceinline__ void gemm_phase(LAS unsigned char* lds, const Gemm g0, const StaticOrder& S, const Epi& E) {
;     ...
;             PG8_LDA(At, 1, 1); PG8_STAGE(PG8_SA(1, 0), a3, voffA);
;             PG8_BAR; PG8_WAIT_L(0); PG8_MMA(1, 0, At, B0); PG8_BAR; PG8_SCHED;
;             PG8_STAGE(PG8_SB(1, 1), b3 + hstep, voffB);
;             PG8_WAIT_V(6); PG8_BAR; PG8_MMA(1, 1, At, B1); PG8_BAR;
;         }
	ds_read_b128 v[146:149], v208 offset:49152
	ds_read_b128 v[150:153], v208 offset:50176
	ds_read_b128 v[154:157], v208 offset:51200
	ds_read_b128 v[162:165], v208 offset:52224
	ds_read_b128 v[170:173], v208 offset:53248
	ds_read_b128 v[184:187], v208 offset:54272
	ds_read_b128 v[188:191], v208 offset:55296
	ds_read_b128 v[192:195], v208 offset:56320
	global_load_lds_dwordx4 v226, s[80:81]
	s_mov_b32 m0, s84
	s_nop 0
	global_load_lds_dwordx4 v228, s[80:81]
	s_barrier
	s_waitcnt lgkmcnt(0)
	v_mfma_f32_16x16x32_f16 v[62:65], v[130:133], v[146:149], v[62:65]
	v_mfma_f32_16x16x32_f16 v[58:61], v[138:141], v[146:149], v[58:61]
	v_mfma_f32_16x16x32_f16 v[46:49], v[130:133], v[154:157], v[46:49]
	v_mfma_f32_16x16x32_f16 v[42:45], v[138:141], v[154:157], v[42:45]
	v_mfma_f32_16x16x32_f16 v[30:33], v[130:133], v[170:173], v[30:33]
	v_mfma_f32_16x16x32_f16 v[26:29], v[138:141], v[170:173], v[26:29]
	v_mfma_f32_16x16x32_f16 v[14:17], v[130:133], v[188:191], v[14:17]
	v_mfma_f32_16x16x32_f16 v[10:13], v[138:141], v[188:191], v[10:13]
	v_mfma_f32_16x16x32_f16 v[62:65], v[134:137], v[150:153], v[62:65]
	v_mfma_f32_16x16x32_f16 v[58:61], v[142:145], v[150:153], v[58:61]
	v_mfma_f32_16x16x32_f16 v[46:49], v[134:137], v[162:165], v[46:49]
	v_mfma_f32_16x16x32_f16 v[42:45], v[142:145], v[162:165], v[42:45]
	v_mfma_f32_16x16x32_f16 v[30:33], v[134:137], v[184:187], v[30:33]
	v_mfma_f32_16x16x32_f16 v[26:29], v[142:145], v[184:187], v[26:29]
	v_mfma_f32_16x16x32_f16 v[14:17], v[134:137], v[192:195], v[14:17]
	v_mfma_f32_16x16x32_f16 v[10:13], v[142:145], v[192:195], v[10:13]
	s_barrier
	s_add_u32 s12, s62, 0x160080
	s_addc_u32 s13, s63, 0
	s_add_i32 m0, s19, 0x1c000
	s_nop 0
	global_load_lds_dwordx4 v174, s[12:13]
	s_add_i32 m0, s19, 0x1e000
	s_nop 0
	global_load_lds_dwordx4 v158, s[12:13]
	s_waitcnt vmcnt(6)
	s_barrier
	v_mfma_f32_16x16x32_f16 v[54:57], v[196:199], v[146:149], v[54:57]
	v_mfma_f32_16x16x32_f16 v[50:53], v[214:217], v[146:149], v[50:53]
	v_mfma_f32_16x16x32_f16 v[38:41], v[196:199], v[154:157], v[38:41]
	v_mfma_f32_16x16x32_f16 v[34:37], v[214:217], v[154:157], v[34:37]
	v_mfma_f32_16x16x32_f16 v[22:25], v[196:199], v[170:173], v[22:25]
	v_mfma_f32_16x16x32_f16 v[18:21], v[214:217], v[170:173], v[18:21]
	v_mfma_f32_16x16x32_f16 v[6:9], v[196:199], v[188:191], v[6:9]
	v_mfma_f32_16x16x32_f16 v[2:5], v[214:217], v[188:191], v[2:5]
	v_mfma_f32_16x16x32_f16 v[54:57], v[210:213], v[150:153], v[54:57]
	v_mfma_f32_16x16x32_f16 v[50:53], v[222:225], v[150:153], v[50:53]
	v_mfma_f32_16x16x32_f16 v[38:41], v[210:213], v[162:165], v[38:41]
	v_mfma_f32_16x16x32_f16 v[34:37], v[222:225], v[162:165], v[34:37]
	v_mfma_f32_16x16x32_f16 v[22:25], v[210:213], v[184:187], v[22:25]
	v_mfma_f32_16x16x32_f16 v[18:21], v[222:225], v[184:187], v[18:21]
	v_mfma_f32_16x16x32_f16 v[6:9], v[210:213], v[192:195], v[6:9]
	v_mfma_f32_16x16x32_f16 v[2:5], v[222:225], v[192:195], v[2:5]
	s_add_i32 s22, s22, 2
	s_add_u32 s24, s24, 0x100
	s_addc_u32 s25, s25, 0
	s_cmpk_gt_u32 s22, 0x55
	s_mov_b64 s[12:13], s[10:11]
	s_barrier
	s_cbranch_scc0 .LBB0_672
	s_lshl_b32 s10, s92, 8
	s_or_b32 s12, s10, s82
	v_add_u32_e32 v130, s12, v204
	v_ashrrev_i32_e32 v131, 31, v130
	v_lshlrev_b64 v[132:133], 2, v[130:131]
	v_lshl_add_u64 v[134:135], s[38:39], 0, v[132:133]
	v_lshl_add_u64 v[132:133], s[48:49], 0, v[132:133]
	global_load_dword v146, v[134:135], off
	global_load_dword v147, v[132:133], off
	v_readlane_b32 s22, v254, 55
	v_readlane_b32 s23, v254, 56
	s_andn2_b64 vcc, exec, s[22:23]
	v_mov_b32_e32 v148, 0
	v_cndmask_b32_e64 v132, 0, 1, s[22:23]
	v_cmp_ne_u32_e64 s[10:11], 1, v132
	s_cbranch_vccnz .LBB0_675
	v_lshl_add_u64 v[130:131], v[130:131], 2, s[50:51]
	global_load_dword v148, v[130:131], off
